# barrier trims + fix-up pieces up front + K-loop first iteration peeled (C=0 instead of 128 zeroing moves per unit)
# baseline (speedup 1.0000x reference)
.LBB0_261:
	s_ashr_i32 s35, s34, 31
	s_lshl_b64 vcc, s[34:35], 21
	s_add_u32 s13, s30, vcc_lo
	s_addc_u32 s15, s31, vcc_hi
	s_add_u32 s54, s13, s54
	s_addc_u32 s55, s15, s55
	s_and_b64 s[86:87], s[86:87], exec
	s_cselect_b32 s13, s55, s11
	s_cselect_b32 s15, s54, s10
	s_add_i32 s35, s19, -2
	s_add_u32 s40, s10, 0x100
	s_addc_u32 s49, s11, 0
	s_add_u32 s10, s38, 0x100080
	s_addc_u32 s11, s39, 0
	s_mov_b32 s38, 0
	s_add_i32 vcc_lo, s38, 2
	s_add_u32 s39, s10, 0xfff00080
	s_addc_u32 s66, s11, -1
	s_add_i32 s67, 0, 0x10000
	s_cmp_eq_u32 s35, s38
	s_cselect_b32 s87, s53, s66
	s_cselect_b32 s86, s52, s39
	s_cselect_b32 s39, s13, s49
	s_cselect_b32 s38, s15, s40
	s_add_i32 vcc_hi, 0, 0x14000
	v_add_u32_e32 v142, s67, v1
	v_add_u32_e32 v180, vcc_hi, v1
	ds_read_b128 v[130:133], v142
	ds_read_b128 v[134:137], v142 offset:1024
	ds_read_b128 v[138:141], v142 offset:2048
	ds_read_b128 v[142:145], v142 offset:3072
	ds_read_b128 v[168:171], v180
	ds_read_b128 v[172:175], v180 offset:1024
	ds_read_b128 v[176:179], v180 offset:2048
	ds_read_b128 v[180:183], v180 offset:3072
	v_lshl_add_u64 v[184:185], s[10:11], 0, v[164:165]
	s_add_i32 m0, s85, 0xc000
	ds_read_b128 v[198:201], v197
	ds_read_b128 v[202:205], v197 offset:1024
	ds_read_b128 v[206:209], v197 offset:2048
	ds_read_b128 v[210:213], v197 offset:3072
	ds_read_b128 v[214:217], v197 offset:4096
	ds_read_b128 v[218:221], v197 offset:5120
	ds_read_b128 v[222:225], v197 offset:6144
	ds_read_b128 v[226:229], v197 offset:7168
	global_load_lds_dwordx4 v[184:185], off
	v_lshl_add_u64 v[184:185], s[10:11], 0, v[166:167]
	s_add_i32 m0, s85, 0xe000
	s_nop 0
	global_load_lds_dwordx4 v[184:185], off
	s_waitcnt vmcnt(8)
	s_waitcnt lgkmcnt(0)
	s_setprio 1
	s_barrier
	v_mfma_f32_16x16x32_bf16 v[114:117], v[130:133], v[198:201], 0
	v_mfma_f32_16x16x32_bf16 v[118:121], v[138:141], v[198:201], 0
	v_mfma_f32_16x16x32_bf16 v[102:105], v[130:133], v[206:209], 0
	v_mfma_f32_16x16x32_bf16 v[98:101], v[138:141], v[206:209], 0
	v_mfma_f32_16x16x32_bf16 v[86:89], v[130:133], v[214:217], 0
	v_mfma_f32_16x16x32_bf16 v[82:85], v[138:141], v[214:217], 0
	v_mfma_f32_16x16x32_bf16 v[54:57], v[130:133], v[222:225], 0
	v_mfma_f32_16x16x32_bf16 v[50:53], v[138:141], v[222:225], 0
	v_mfma_f32_16x16x32_bf16 v[114:117], v[134:137], v[202:205], v[114:117]
	v_mfma_f32_16x16x32_bf16 v[118:121], v[142:145], v[202:205], v[118:121]
	v_mfma_f32_16x16x32_bf16 v[102:105], v[134:137], v[210:213], v[102:105]
	v_mfma_f32_16x16x32_bf16 v[98:101], v[142:145], v[210:213], v[98:101]
	v_mfma_f32_16x16x32_bf16 v[86:89], v[134:137], v[218:221], v[86:89]
	v_mfma_f32_16x16x32_bf16 v[82:85], v[142:145], v[218:221], v[82:85]
	v_mfma_f32_16x16x32_bf16 v[54:57], v[134:137], v[226:229], v[54:57]
	v_mfma_f32_16x16x32_bf16 v[50:53], v[142:145], v[226:229], v[50:53]
	s_setprio 0
	s_setprio 1
	v_mfma_f32_16x16x32_bf16 v[126:129], v[168:171], v[198:201], 0
	v_mfma_f32_16x16x32_bf16 v[122:125], v[176:179], v[198:201], 0
	v_mfma_f32_16x16x32_bf16 v[110:113], v[168:171], v[206:209], 0
	v_mfma_f32_16x16x32_bf16 v[106:109], v[176:179], v[206:209], 0
	v_mfma_f32_16x16x32_bf16 v[94:97], v[168:171], v[214:217], 0
	v_mfma_f32_16x16x32_bf16 v[90:93], v[176:179], v[214:217], 0
	v_mfma_f32_16x16x32_bf16 v[70:73], v[168:171], v[222:225], 0
	v_mfma_f32_16x16x32_bf16 v[66:69], v[176:179], v[222:225], 0
	v_mfma_f32_16x16x32_bf16 v[126:129], v[172:175], v[202:205], v[126:129]
	v_mfma_f32_16x16x32_bf16 v[122:125], v[180:183], v[202:205], v[122:125]
	v_mfma_f32_16x16x32_bf16 v[110:113], v[172:175], v[210:213], v[110:113]
	v_mfma_f32_16x16x32_bf16 v[106:109], v[180:183], v[210:213], v[106:109]
	v_mfma_f32_16x16x32_bf16 v[94:97], v[172:175], v[218:221], v[94:97]
	v_mfma_f32_16x16x32_bf16 v[90:93], v[180:183], v[218:221], v[90:93]
	v_mfma_f32_16x16x32_bf16 v[70:73], v[172:175], v[226:229], v[70:73]
	v_mfma_f32_16x16x32_bf16 v[66:69], v[180:183], v[226:229], v[66:69]
	s_barrier
	s_setprio 0
	s_add_i32 s66, s67, s97
	v_lshl_add_u64 v[184:185], s[38:39], 0, v[156:157]
	s_mov_b32 m0, s66
	ds_read_b128 v[198:201], v197 offset:16384
	ds_read_b128 v[202:205], v197 offset:17408
	ds_read_b128 v[206:209], v197 offset:18432
	ds_read_b128 v[210:213], v197 offset:19456
	ds_read_b128 v[214:217], v197 offset:20480
	ds_read_b128 v[218:221], v197 offset:21504
	ds_read_b128 v[222:225], v197 offset:22528
	ds_read_b128 v[226:229], v197 offset:23552
	global_load_lds_dwordx4 v[184:185], off
	s_add_i32 m0, s66, 0x2000
	s_add_u32 s66, s38, 0x100000
	v_lshl_add_u64 v[230:231], s[38:39], 0, v[160:161]
	s_addc_u32 s67, s39, 0
	s_add_i32 vcc_hi, vcc_hi, s97
	global_load_lds_dwordx4 v[230:231], off
	v_lshl_add_u64 v[232:233], s[66:67], 0, v[156:157]
	s_mov_b32 m0, vcc_hi
	v_lshl_add_u64 v[234:235], s[86:87], 0, v[158:159]
	global_load_lds_dwordx4 v[232:233], off
	v_lshl_add_u64 v[232:233], s[66:67], 0, v[160:161]
	s_add_i32 m0, vcc_hi, 0x2000
	s_nop 0
	global_load_lds_dwordx4 v[232:233], off
	v_lshl_add_u64 v[232:233], s[86:87], 0, v[154:155]
	s_mov_b32 m0, s85
	s_nop 0
	global_load_lds_dwordx4 v[232:233], off
	s_mov_b32 m0, s92
	s_nop 0
	global_load_lds_dwordx4 v[234:235], off
	s_waitcnt vmcnt(8)
	s_waitcnt lgkmcnt(0)
	s_setprio 1
	s_barrier
	v_mfma_f32_16x16x32_bf16 v[62:65], v[130:133], v[198:201], 0
	v_mfma_f32_16x16x32_bf16 v[58:61], v[138:141], v[198:201], 0
	v_mfma_f32_16x16x32_bf16 v[38:41], v[130:133], v[206:209], 0
	v_mfma_f32_16x16x32_bf16 v[34:37], v[138:141], v[206:209], 0
	v_mfma_f32_16x16x32_bf16 v[22:25], v[130:133], v[214:217], 0
	v_mfma_f32_16x16x32_bf16 v[18:21], v[138:141], v[214:217], 0
	v_mfma_f32_16x16x32_bf16 v[6:9], v[130:133], v[222:225], 0
	v_mfma_f32_16x16x32_bf16 v[2:5], v[138:141], v[222:225], 0
	v_mfma_f32_16x16x32_bf16 v[62:65], v[134:137], v[202:205], v[62:65]
	v_mfma_f32_16x16x32_bf16 v[58:61], v[142:145], v[202:205], v[58:61]
	v_mfma_f32_16x16x32_bf16 v[38:41], v[134:137], v[210:213], v[38:41]
	v_mfma_f32_16x16x32_bf16 v[34:37], v[142:145], v[210:213], v[34:37]
	v_mfma_f32_16x16x32_bf16 v[22:25], v[134:137], v[218:221], v[22:25]
	v_mfma_f32_16x16x32_bf16 v[18:21], v[142:145], v[218:221], v[18:21]
	v_mfma_f32_16x16x32_bf16 v[6:9], v[134:137], v[226:229], v[6:9]
	v_mfma_f32_16x16x32_bf16 v[2:5], v[142:145], v[226:229], v[2:5]
	s_setprio 0
	s_setprio 1
	v_mfma_f32_16x16x32_bf16 v[78:81], v[168:171], v[198:201], 0
	v_mfma_f32_16x16x32_bf16 v[74:77], v[176:179], v[198:201], 0
	v_mfma_f32_16x16x32_bf16 v[46:49], v[168:171], v[206:209], 0
	v_mfma_f32_16x16x32_bf16 v[42:45], v[176:179], v[206:209], 0
	v_mfma_f32_16x16x32_bf16 v[30:33], v[168:171], v[214:217], 0
	v_mfma_f32_16x16x32_bf16 v[26:29], v[176:179], v[214:217], 0
	v_mfma_f32_16x16x32_bf16 v[14:17], v[168:171], v[222:225], 0
	v_mfma_f32_16x16x32_bf16 v[10:13], v[176:179], v[222:225], 0
	v_mfma_f32_16x16x32_bf16 v[78:81], v[172:175], v[202:205], v[78:81]
	v_mfma_f32_16x16x32_bf16 v[74:77], v[180:183], v[202:205], v[74:77]
	v_mfma_f32_16x16x32_bf16 v[46:49], v[172:175], v[210:213], v[46:49]
	v_mfma_f32_16x16x32_bf16 v[42:45], v[180:183], v[210:213], v[42:45]
	v_mfma_f32_16x16x32_bf16 v[30:33], v[172:175], v[218:221], v[30:33]
	v_mfma_f32_16x16x32_bf16 v[26:29], v[180:183], v[218:221], v[26:29]
	v_mfma_f32_16x16x32_bf16 v[14:17], v[172:175], v[226:229], v[14:17]
	v_mfma_f32_16x16x32_bf16 v[10:13], v[180:183], v[226:229], v[10:13]
	s_barrier
	s_setprio 0
	s_add_i32 vcc_hi, 0, 0x18000
	s_add_i32 s56, 0, 0x1c000
	v_add_u32_e32 v142, vcc_hi, v1
	v_add_u32_e32 v180, s56, v1
	ds_read_b128 v[130:133], v142
	ds_read_b128 v[134:137], v142 offset:1024
	ds_read_b128 v[138:141], v142 offset:2048
	ds_read_b128 v[142:145], v142 offset:3072
	ds_read_b128 v[168:171], v180
	ds_read_b128 v[172:175], v180 offset:1024
	ds_read_b128 v[176:179], v180 offset:2048
	ds_read_b128 v[180:183], v180 offset:3072
	s_add_u32 s66, s86, 0x100000
	s_addc_u32 s67, s87, 0
	s_mov_b32 m0, s93
	v_lshl_add_u64 v[236:237], s[66:67], 0, v[154:155]
	ds_read_b128 v[198:201], v197 offset:32768
	ds_read_b128 v[202:205], v197 offset:33792
	ds_read_b128 v[206:209], v197 offset:34816
	ds_read_b128 v[210:213], v197 offset:35840
	ds_read_b128 v[214:217], v197 offset:36864
	ds_read_b128 v[218:221], v197 offset:37888
	ds_read_b128 v[222:225], v197 offset:38912
	ds_read_b128 v[226:229], v197 offset:39936
	global_load_lds_dwordx4 v[236:237], off
	v_lshl_add_u64 v[236:237], s[66:67], 0, v[158:159]
	s_mov_b32 m0, s42
	s_nop 0
	global_load_lds_dwordx4 v[236:237], off
	s_waitcnt vmcnt(8)
	s_waitcnt lgkmcnt(0)
	s_setprio 1
	s_barrier
	v_mfma_f32_16x16x32_bf16 v[114:117], v[130:133], v[198:201], v[114:117]
	v_mfma_f32_16x16x32_bf16 v[118:121], v[138:141], v[198:201], v[118:121]
	v_mfma_f32_16x16x32_bf16 v[102:105], v[130:133], v[206:209], v[102:105]
	v_mfma_f32_16x16x32_bf16 v[98:101], v[138:141], v[206:209], v[98:101]
	v_mfma_f32_16x16x32_bf16 v[86:89], v[130:133], v[214:217], v[86:89]
	v_mfma_f32_16x16x32_bf16 v[82:85], v[138:141], v[214:217], v[82:85]
	v_mfma_f32_16x16x32_bf16 v[54:57], v[130:133], v[222:225], v[54:57]
	v_mfma_f32_16x16x32_bf16 v[50:53], v[138:141], v[222:225], v[50:53]
	v_mfma_f32_16x16x32_bf16 v[114:117], v[134:137], v[202:205], v[114:117]
	v_mfma_f32_16x16x32_bf16 v[118:121], v[142:145], v[202:205], v[118:121]
	v_mfma_f32_16x16x32_bf16 v[102:105], v[134:137], v[210:213], v[102:105]
	v_mfma_f32_16x16x32_bf16 v[98:101], v[142:145], v[210:213], v[98:101]
	v_mfma_f32_16x16x32_bf16 v[86:89], v[134:137], v[218:221], v[86:89]
	v_mfma_f32_16x16x32_bf16 v[82:85], v[142:145], v[218:221], v[82:85]
	v_mfma_f32_16x16x32_bf16 v[54:57], v[134:137], v[226:229], v[54:57]
	v_mfma_f32_16x16x32_bf16 v[50:53], v[142:145], v[226:229], v[50:53]
	s_setprio 0
	s_setprio 1
	v_mfma_f32_16x16x32_bf16 v[126:129], v[168:171], v[198:201], v[126:129]
	v_mfma_f32_16x16x32_bf16 v[122:125], v[176:179], v[198:201], v[122:125]
	v_mfma_f32_16x16x32_bf16 v[110:113], v[168:171], v[206:209], v[110:113]
	v_mfma_f32_16x16x32_bf16 v[106:109], v[176:179], v[206:209], v[106:109]
	v_mfma_f32_16x16x32_bf16 v[94:97], v[168:171], v[214:217], v[94:97]
	v_mfma_f32_16x16x32_bf16 v[90:93], v[176:179], v[214:217], v[90:93]
	v_mfma_f32_16x16x32_bf16 v[70:73], v[168:171], v[222:225], v[70:73]
	v_mfma_f32_16x16x32_bf16 v[66:69], v[176:179], v[222:225], v[66:69]
	v_mfma_f32_16x16x32_bf16 v[126:129], v[172:175], v[202:205], v[126:129]
	v_mfma_f32_16x16x32_bf16 v[122:125], v[180:183], v[202:205], v[122:125]
	v_mfma_f32_16x16x32_bf16 v[110:113], v[172:175], v[210:213], v[110:113]
	v_mfma_f32_16x16x32_bf16 v[106:109], v[180:183], v[210:213], v[106:109]
	v_mfma_f32_16x16x32_bf16 v[94:97], v[172:175], v[218:221], v[94:97]
	v_mfma_f32_16x16x32_bf16 v[90:93], v[180:183], v[218:221], v[90:93]
	v_mfma_f32_16x16x32_bf16 v[70:73], v[172:175], v[226:229], v[70:73]
	v_mfma_f32_16x16x32_bf16 v[66:69], v[180:183], v[226:229], v[66:69]
	s_barrier
	s_setprio 0
	s_add_i32 s57, vcc_hi, s97
	v_lshl_add_u64 v[184:185], v[184:185], 0, s[94:95]
	s_mov_b32 m0, s57
	ds_read_b128 v[198:201], v197 offset:49152
	ds_read_b128 v[202:205], v197 offset:50176
	ds_read_b128 v[206:209], v197 offset:51200
	ds_read_b128 v[210:213], v197 offset:52224
	ds_read_b128 v[214:217], v197 offset:53248
	ds_read_b128 v[218:221], v197 offset:54272
	ds_read_b128 v[222:225], v197 offset:55296
	ds_read_b128 v[226:229], v197 offset:56320
	global_load_lds_dwordx4 v[184:185], off
	s_add_i32 m0, s57, 0x2000
	s_add_u32 s38, s38, 0x100080
	v_lshl_add_u64 v[184:185], v[230:231], 0, s[94:95]
	s_addc_u32 s39, s39, 0
	s_add_i32 s56, s56, s97
	global_load_lds_dwordx4 v[184:185], off
	v_lshl_add_u64 v[184:185], s[38:39], 0, v[156:157]
	s_mov_b32 m0, s56
	s_nop 0
	global_load_lds_dwordx4 v[184:185], off
	v_lshl_add_u64 v[184:185], s[38:39], 0, v[160:161]
	s_add_i32 m0, s56, 0x2000
	s_nop 0
	global_load_lds_dwordx4 v[184:185], off
	v_lshl_add_u64 v[184:185], v[232:233], 0, s[94:95]
	s_mov_b32 m0, s43
	s_nop 0
	global_load_lds_dwordx4 v[184:185], off
	v_lshl_add_u64 v[184:185], v[234:235], 0, s[94:95]
	s_mov_b32 m0, s90
	s_nop 0
	global_load_lds_dwordx4 v[184:185], off
	s_waitcnt vmcnt(8)
	s_waitcnt lgkmcnt(0)
	s_setprio 1
	s_barrier
	v_mfma_f32_16x16x32_bf16 v[62:65], v[130:133], v[198:201], v[62:65]
	v_mfma_f32_16x16x32_bf16 v[58:61], v[138:141], v[198:201], v[58:61]
	v_mfma_f32_16x16x32_bf16 v[38:41], v[130:133], v[206:209], v[38:41]
	v_mfma_f32_16x16x32_bf16 v[34:37], v[138:141], v[206:209], v[34:37]
	v_mfma_f32_16x16x32_bf16 v[22:25], v[130:133], v[214:217], v[22:25]
	v_mfma_f32_16x16x32_bf16 v[18:21], v[138:141], v[214:217], v[18:21]
	v_mfma_f32_16x16x32_bf16 v[6:9], v[130:133], v[222:225], v[6:9]
	v_mfma_f32_16x16x32_bf16 v[2:5], v[138:141], v[222:225], v[2:5]
	v_mfma_f32_16x16x32_bf16 v[62:65], v[134:137], v[202:205], v[62:65]
	v_mfma_f32_16x16x32_bf16 v[58:61], v[142:145], v[202:205], v[58:61]
	v_mfma_f32_16x16x32_bf16 v[38:41], v[134:137], v[210:213], v[38:41]
	v_mfma_f32_16x16x32_bf16 v[34:37], v[142:145], v[210:213], v[34:37]
	v_mfma_f32_16x16x32_bf16 v[22:25], v[134:137], v[218:221], v[22:25]
	v_mfma_f32_16x16x32_bf16 v[18:21], v[142:145], v[218:221], v[18:21]
	v_mfma_f32_16x16x32_bf16 v[6:9], v[134:137], v[226:229], v[6:9]
	v_mfma_f32_16x16x32_bf16 v[2:5], v[142:145], v[226:229], v[2:5]
	s_setprio 0
	s_setprio 1
	v_mfma_f32_16x16x32_bf16 v[78:81], v[168:171], v[198:201], v[78:81]
	v_mfma_f32_16x16x32_bf16 v[74:77], v[176:179], v[198:201], v[74:77]
	v_mfma_f32_16x16x32_bf16 v[46:49], v[168:171], v[206:209], v[46:49]
	v_mfma_f32_16x16x32_bf16 v[42:45], v[176:179], v[206:209], v[42:45]
	v_mfma_f32_16x16x32_bf16 v[30:33], v[168:171], v[214:217], v[30:33]
	v_mfma_f32_16x16x32_bf16 v[26:29], v[176:179], v[214:217], v[26:29]
	v_mfma_f32_16x16x32_bf16 v[14:17], v[168:171], v[222:225], v[14:17]
	v_mfma_f32_16x16x32_bf16 v[10:13], v[176:179], v[222:225], v[10:13]
	v_mfma_f32_16x16x32_bf16 v[78:81], v[172:175], v[202:205], v[78:81]
	v_mfma_f32_16x16x32_bf16 v[74:77], v[180:183], v[202:205], v[74:77]
	v_mfma_f32_16x16x32_bf16 v[46:49], v[172:175], v[210:213], v[46:49]
	v_mfma_f32_16x16x32_bf16 v[42:45], v[180:183], v[210:213], v[42:45]
	v_mfma_f32_16x16x32_bf16 v[30:33], v[172:175], v[218:221], v[30:33]
	v_mfma_f32_16x16x32_bf16 v[26:29], v[180:183], v[218:221], v[26:29]
	v_mfma_f32_16x16x32_bf16 v[14:17], v[172:175], v[226:229], v[14:17]
	v_mfma_f32_16x16x32_bf16 v[10:13], v[180:183], v[226:229], v[10:13]
	s_barrier
	s_setprio 0
	s_add_u32 s40, s40, 0x100
	s_addc_u32 s49, s49, 0
	s_add_u32 s10, s10, 0x100
	s_addc_u32 s11, s11, 0
	s_cmp_ge_u32 vcc_lo, s19
	s_mov_b32 s38, vcc_lo
	s_cbranch_scc1 .Lpeel_done_0

.Lpeel_done_0:
	v_readlane_b32 s10, v254, 27
	v_readlane_b32 s11, v254, 28
	s_and_b64 vcc, exec, s[10:11]
	s_cbranch_vccz .LBB0_270
	s_barrier
	s_cmp_lt_i32 s18, 0
	s_mov_b64 s[10:11], -1
	s_cbranch_scc1 .LBB0_271

.LBB0_1692:
	s_ashr_i32 s13, s12, 31
	s_lshl_b64 s[16:17], s[12:13], 18
	s_add_u32 s16, s45, s16
	s_addc_u32 s17, s44, s17
	s_and_b64 s[26:27], s[26:27], exec
	s_cselect_b32 s13, s17, s25
	s_cselect_b32 s15, s16, s24
	s_add_u32 s34, s24, 0x100
	s_addc_u32 s35, s25, 0
	s_add_u32 s22, s22, 0x80080
	s_addc_u32 s23, s23, 0
	s_mov_b32 s36, -2
	ds_read_b128 v[128:131], v169
	ds_read_b128 v[132:135], v169 offset:1024
	ds_read_b128 v[136:139], v169 offset:2048
	ds_read_b128 v[140:143], v169 offset:3072
	ds_read_b128 v[158:161], v170
	ds_read_b128 v[162:165], v170 offset:1024
	ds_read_b128 v[172:175], v170 offset:2048
	ds_read_b128 v[176:179], v170 offset:3072
	s_add_u32 s24, s22, 0xfff80080
	s_addc_u32 s25, s23, -1
	s_cmp_eq_u32 s36, 4
	s_cselect_b32 s27, s5, s25
	s_cselect_b32 s26, s4, s24
	s_cselect_b32 s25, s13, s35
	s_cselect_b32 s24, s15, s34
	v_lshl_add_u64 v[212:213], s[22:23], 0, v[152:153]
	s_add_i32 m0, s94, 0xc000
	ds_read_b128 v[180:183], v171
	ds_read_b128 v[184:187], v171 offset:1024
	ds_read_b128 v[188:191], v171 offset:2048
	ds_read_b128 v[192:195], v171 offset:3072
	ds_read_b128 v[196:199], v171 offset:4096
	ds_read_b128 v[200:203], v171 offset:5120
	ds_read_b128 v[204:207], v171 offset:6144
	ds_read_b128 v[208:211], v171 offset:7168
	global_load_lds_dwordx4 v[212:213], off
	v_lshl_add_u64 v[212:213], s[22:23], 0, v[154:155]
	s_add_i32 m0, s94, 0xe000
	s_nop 0
	global_load_lds_dwordx4 v[212:213], off
	s_waitcnt vmcnt(8)
	s_waitcnt lgkmcnt(0)
	s_setprio 1
	s_barrier
	v_mfma_f32_16x16x32_bf16 v[80:83], v[128:131], v[180:183], 0
	v_mfma_f32_16x16x32_bf16 v[92:95], v[136:139], v[180:183], 0
	v_mfma_f32_16x16x32_bf16 v[84:87], v[128:131], v[188:191], 0
	v_mfma_f32_16x16x32_bf16 v[96:99], v[136:139], v[188:191], 0
	v_mfma_f32_16x16x32_bf16 v[88:91], v[128:131], v[196:199], 0
	v_mfma_f32_16x16x32_bf16 v[100:103], v[136:139], v[196:199], 0
	v_mfma_f32_16x16x32_bf16 v[72:75], v[128:131], v[204:207], 0
	v_mfma_f32_16x16x32_bf16 v[76:79], v[136:139], v[204:207], 0
	v_mfma_f32_16x16x32_bf16 v[80:83], v[132:135], v[184:187], v[80:83]
	v_mfma_f32_16x16x32_bf16 v[92:95], v[140:143], v[184:187], v[92:95]
	v_mfma_f32_16x16x32_bf16 v[84:87], v[132:135], v[192:195], v[84:87]
	v_mfma_f32_16x16x32_bf16 v[96:99], v[140:143], v[192:195], v[96:99]
	v_mfma_f32_16x16x32_bf16 v[88:91], v[132:135], v[200:203], v[88:91]
	v_mfma_f32_16x16x32_bf16 v[100:103], v[140:143], v[200:203], v[100:103]
	v_mfma_f32_16x16x32_bf16 v[72:75], v[132:135], v[208:211], v[72:75]
	v_mfma_f32_16x16x32_bf16 v[76:79], v[140:143], v[208:211], v[76:79]
	s_setprio 0
	s_setprio 1
	v_mfma_f32_16x16x32_bf16 v[104:107], v[158:161], v[180:183], 0
	v_mfma_f32_16x16x32_bf16 v[116:119], v[172:175], v[180:183], 0
	v_mfma_f32_16x16x32_bf16 v[108:111], v[158:161], v[188:191], 0
	v_mfma_f32_16x16x32_bf16 v[120:123], v[172:175], v[188:191], 0
	v_mfma_f32_16x16x32_bf16 v[112:115], v[158:161], v[196:199], 0
	v_mfma_f32_16x16x32_bf16 v[124:127], v[172:175], v[196:199], 0
	v_mfma_f32_16x16x32_bf16 v[68:71], v[158:161], v[204:207], 0
	v_mfma_f32_16x16x32_bf16 v[64:67], v[172:175], v[204:207], 0
	v_mfma_f32_16x16x32_bf16 v[104:107], v[162:165], v[184:187], v[104:107]
	v_mfma_f32_16x16x32_bf16 v[116:119], v[176:179], v[184:187], v[116:119]
	v_mfma_f32_16x16x32_bf16 v[108:111], v[162:165], v[192:195], v[108:111]
	v_mfma_f32_16x16x32_bf16 v[120:123], v[176:179], v[192:195], v[120:123]
	v_mfma_f32_16x16x32_bf16 v[112:115], v[162:165], v[200:203], v[112:115]
	v_mfma_f32_16x16x32_bf16 v[124:127], v[176:179], v[200:203], v[124:127]
	v_mfma_f32_16x16x32_bf16 v[68:71], v[162:165], v[208:211], v[68:71]
	v_mfma_f32_16x16x32_bf16 v[64:67], v[176:179], v[208:211], v[64:67]
	s_barrier
	s_setprio 0
	s_add_i32 s37, s31, s97
	v_lshl_add_u64 v[212:213], s[24:25], 0, v[148:149]
	s_mov_b32 m0, s37
	ds_read_b128 v[180:183], v171 offset:16384
	ds_read_b128 v[184:187], v171 offset:17408
	ds_read_b128 v[188:191], v171 offset:18432
	ds_read_b128 v[192:195], v171 offset:19456
	ds_read_b128 v[196:199], v171 offset:20480
	ds_read_b128 v[200:203], v171 offset:21504
	ds_read_b128 v[204:207], v171 offset:22528
	ds_read_b128 v[208:211], v171 offset:23552
	global_load_lds_dwordx4 v[212:213], off
	s_add_i32 m0, s37, 0x2000
	s_add_u32 s38, s24, 0x20000
	v_lshl_add_u64 v[214:215], s[24:25], 0, v[144:145]
	s_addc_u32 s39, s25, 0
	s_add_i32 s37, s33, s97
	global_load_lds_dwordx4 v[214:215], off
	v_lshl_add_u64 v[216:217], s[38:39], 0, v[148:149]
	s_mov_b32 m0, s37
	v_lshl_add_u64 v[218:219], s[26:27], 0, v[146:147]
	global_load_lds_dwordx4 v[216:217], off
	v_lshl_add_u64 v[216:217], s[38:39], 0, v[144:145]
	s_add_i32 m0, s37, 0x2000
	s_nop 0
	global_load_lds_dwordx4 v[216:217], off
	v_lshl_add_u64 v[216:217], s[26:27], 0, v[150:151]
	s_mov_b32 m0, s94
	s_nop 0
	global_load_lds_dwordx4 v[216:217], off
	s_mov_b32 m0, s3
	s_nop 0
	global_load_lds_dwordx4 v[218:219], off
	s_waitcnt vmcnt(8)
	s_waitcnt lgkmcnt(0)
	s_setprio 1
	s_barrier
	v_mfma_f32_16x16x32_bf16 v[48:51], v[128:131], v[180:183], 0
	v_mfma_f32_16x16x32_bf16 v[52:55], v[136:139], v[180:183], 0
	v_mfma_f32_16x16x32_bf16 v[32:35], v[128:131], v[188:191], 0
	v_mfma_f32_16x16x32_bf16 v[36:39], v[136:139], v[188:191], 0
	v_mfma_f32_16x16x32_bf16 v[16:19], v[128:131], v[196:199], 0
	v_mfma_f32_16x16x32_bf16 v[20:23], v[136:139], v[196:199], 0
	v_mfma_f32_16x16x32_bf16 v[0:3], v[128:131], v[204:207], 0
	v_mfma_f32_16x16x32_bf16 v[4:7], v[136:139], v[204:207], 0
	v_mfma_f32_16x16x32_bf16 v[48:51], v[132:135], v[184:187], v[48:51]
	v_mfma_f32_16x16x32_bf16 v[52:55], v[140:143], v[184:187], v[52:55]
	v_mfma_f32_16x16x32_bf16 v[32:35], v[132:135], v[192:195], v[32:35]
	v_mfma_f32_16x16x32_bf16 v[36:39], v[140:143], v[192:195], v[36:39]
	v_mfma_f32_16x16x32_bf16 v[16:19], v[132:135], v[200:203], v[16:19]
	v_mfma_f32_16x16x32_bf16 v[20:23], v[140:143], v[200:203], v[20:23]
	v_mfma_f32_16x16x32_bf16 v[0:3], v[132:135], v[208:211], v[0:3]
	v_mfma_f32_16x16x32_bf16 v[4:7], v[140:143], v[208:211], v[4:7]
	s_setprio 0
	s_setprio 1
	v_mfma_f32_16x16x32_bf16 v[56:59], v[158:161], v[180:183], 0
	v_mfma_f32_16x16x32_bf16 v[60:63], v[172:175], v[180:183], 0
	v_mfma_f32_16x16x32_bf16 v[40:43], v[158:161], v[188:191], 0
	v_mfma_f32_16x16x32_bf16 v[44:47], v[172:175], v[188:191], 0
	v_mfma_f32_16x16x32_bf16 v[24:27], v[158:161], v[196:199], 0
	v_mfma_f32_16x16x32_bf16 v[28:31], v[172:175], v[196:199], 0
	v_mfma_f32_16x16x32_bf16 v[8:11], v[158:161], v[204:207], 0
	v_mfma_f32_16x16x32_bf16 v[12:15], v[172:175], v[204:207], 0
	v_mfma_f32_16x16x32_bf16 v[56:59], v[162:165], v[184:187], v[56:59]
	v_mfma_f32_16x16x32_bf16 v[60:63], v[176:179], v[184:187], v[60:63]
	v_mfma_f32_16x16x32_bf16 v[40:43], v[162:165], v[192:195], v[40:43]
	v_mfma_f32_16x16x32_bf16 v[44:47], v[176:179], v[192:195], v[44:47]
	v_mfma_f32_16x16x32_bf16 v[24:27], v[162:165], v[200:203], v[24:27]
	v_mfma_f32_16x16x32_bf16 v[28:31], v[176:179], v[200:203], v[28:31]
	v_mfma_f32_16x16x32_bf16 v[8:11], v[162:165], v[208:211], v[8:11]
	v_mfma_f32_16x16x32_bf16 v[12:15], v[176:179], v[208:211], v[12:15]
	s_barrier
	s_setprio 0
	s_add_i32 s37, 0, 0x18000
	s_add_i32 s38, 0, 0x1c000
	v_add_u32_e32 v140, s37, v167
	v_add_u32_e32 v176, s38, v167
	ds_read_b128 v[128:131], v140
	ds_read_b128 v[132:135], v140 offset:1024
	ds_read_b128 v[136:139], v140 offset:2048
	ds_read_b128 v[140:143], v140 offset:3072
	ds_read_b128 v[158:161], v176
	ds_read_b128 v[162:165], v176 offset:1024
	ds_read_b128 v[172:175], v176 offset:2048
	ds_read_b128 v[176:179], v176 offset:3072
	s_add_u32 s26, s26, 0x80000
	s_addc_u32 s27, s27, 0
	s_mov_b32 m0, s7
	v_lshl_add_u64 v[220:221], s[26:27], 0, v[150:151]
	ds_read_b128 v[180:183], v171 offset:32768
	ds_read_b128 v[184:187], v171 offset:33792
	ds_read_b128 v[188:191], v171 offset:34816
	ds_read_b128 v[192:195], v171 offset:35840
	ds_read_b128 v[196:199], v171 offset:36864
	ds_read_b128 v[200:203], v171 offset:37888
	ds_read_b128 v[204:207], v171 offset:38912
	ds_read_b128 v[208:211], v171 offset:39936
	global_load_lds_dwordx4 v[220:221], off
	v_lshl_add_u64 v[220:221], s[26:27], 0, v[146:147]
	s_mov_b32 m0, s19
	s_nop 0
	global_load_lds_dwordx4 v[220:221], off
	s_waitcnt vmcnt(8)
	s_waitcnt lgkmcnt(0)
	s_setprio 1
	s_barrier
	v_mfma_f32_16x16x32_bf16 v[80:83], v[128:131], v[180:183], v[80:83]
	v_mfma_f32_16x16x32_bf16 v[92:95], v[136:139], v[180:183], v[92:95]
	v_mfma_f32_16x16x32_bf16 v[84:87], v[128:131], v[188:191], v[84:87]
	v_mfma_f32_16x16x32_bf16 v[96:99], v[136:139], v[188:191], v[96:99]
	v_mfma_f32_16x16x32_bf16 v[88:91], v[128:131], v[196:199], v[88:91]
	v_mfma_f32_16x16x32_bf16 v[100:103], v[136:139], v[196:199], v[100:103]
	v_mfma_f32_16x16x32_bf16 v[72:75], v[128:131], v[204:207], v[72:75]
	v_mfma_f32_16x16x32_bf16 v[76:79], v[136:139], v[204:207], v[76:79]
	v_mfma_f32_16x16x32_bf16 v[80:83], v[132:135], v[184:187], v[80:83]
	v_mfma_f32_16x16x32_bf16 v[92:95], v[140:143], v[184:187], v[92:95]
	v_mfma_f32_16x16x32_bf16 v[84:87], v[132:135], v[192:195], v[84:87]
	v_mfma_f32_16x16x32_bf16 v[96:99], v[140:143], v[192:195], v[96:99]
	v_mfma_f32_16x16x32_bf16 v[88:91], v[132:135], v[200:203], v[88:91]
	v_mfma_f32_16x16x32_bf16 v[100:103], v[140:143], v[200:203], v[100:103]
	v_mfma_f32_16x16x32_bf16 v[72:75], v[132:135], v[208:211], v[72:75]
	v_mfma_f32_16x16x32_bf16 v[76:79], v[140:143], v[208:211], v[76:79]
	s_setprio 0
	s_setprio 1
	v_mfma_f32_16x16x32_bf16 v[104:107], v[158:161], v[180:183], v[104:107]
	v_mfma_f32_16x16x32_bf16 v[116:119], v[172:175], v[180:183], v[116:119]
	v_mfma_f32_16x16x32_bf16 v[108:111], v[158:161], v[188:191], v[108:111]
	v_mfma_f32_16x16x32_bf16 v[120:123], v[172:175], v[188:191], v[120:123]
	v_mfma_f32_16x16x32_bf16 v[112:115], v[158:161], v[196:199], v[112:115]
	v_mfma_f32_16x16x32_bf16 v[124:127], v[172:175], v[196:199], v[124:127]
	v_mfma_f32_16x16x32_bf16 v[68:71], v[158:161], v[204:207], v[68:71]
	v_mfma_f32_16x16x32_bf16 v[64:67], v[172:175], v[204:207], v[64:67]
	v_mfma_f32_16x16x32_bf16 v[104:107], v[162:165], v[184:187], v[104:107]
	v_mfma_f32_16x16x32_bf16 v[116:119], v[176:179], v[184:187], v[116:119]
	v_mfma_f32_16x16x32_bf16 v[108:111], v[162:165], v[192:195], v[108:111]
	v_mfma_f32_16x16x32_bf16 v[120:123], v[176:179], v[192:195], v[120:123]
	v_mfma_f32_16x16x32_bf16 v[112:115], v[162:165], v[200:203], v[112:115]
	v_mfma_f32_16x16x32_bf16 v[124:127], v[176:179], v[200:203], v[124:127]
	v_mfma_f32_16x16x32_bf16 v[68:71], v[162:165], v[208:211], v[68:71]
	v_mfma_f32_16x16x32_bf16 v[64:67], v[176:179], v[208:211], v[64:67]
	s_barrier
	s_setprio 0
	s_add_i32 s26, s37, s97
	v_lshl_add_u64 v[212:213], v[212:213], 0, s[0:1]
	s_mov_b32 m0, s26
	ds_read_b128 v[180:183], v171 offset:49152
	ds_read_b128 v[184:187], v171 offset:50176
	ds_read_b128 v[188:191], v171 offset:51200
	ds_read_b128 v[192:195], v171 offset:52224
	ds_read_b128 v[196:199], v171 offset:53248
	ds_read_b128 v[200:203], v171 offset:54272
	ds_read_b128 v[204:207], v171 offset:55296
	ds_read_b128 v[208:211], v171 offset:56320
	global_load_lds_dwordx4 v[212:213], off
	s_add_i32 m0, s26, 0x2000
	s_add_u32 s24, s24, 0x20080
	v_lshl_add_u64 v[212:213], v[214:215], 0, s[0:1]
	s_addc_u32 s25, s25, 0
	s_add_i32 s26, s38, s97
	global_load_lds_dwordx4 v[212:213], off
	v_lshl_add_u64 v[212:213], s[24:25], 0, v[148:149]
	s_mov_b32 m0, s26
	s_nop 0
	global_load_lds_dwordx4 v[212:213], off
	v_lshl_add_u64 v[212:213], s[24:25], 0, v[144:145]
	s_add_i32 m0, s26, 0x2000
	s_nop 0
	global_load_lds_dwordx4 v[212:213], off
	v_lshl_add_u64 v[212:213], v[216:217], 0, s[0:1]
	s_mov_b32 m0, s28
	s_nop 0
	global_load_lds_dwordx4 v[212:213], off
	v_lshl_add_u64 v[212:213], v[218:219], 0, s[0:1]
	s_mov_b32 m0, s29
	s_nop 0
	global_load_lds_dwordx4 v[212:213], off
	s_waitcnt vmcnt(8)
	s_waitcnt lgkmcnt(0)
	s_setprio 1
	s_barrier
	v_mfma_f32_16x16x32_bf16 v[48:51], v[128:131], v[180:183], v[48:51]
	v_mfma_f32_16x16x32_bf16 v[52:55], v[136:139], v[180:183], v[52:55]
	v_mfma_f32_16x16x32_bf16 v[32:35], v[128:131], v[188:191], v[32:35]
	v_mfma_f32_16x16x32_bf16 v[36:39], v[136:139], v[188:191], v[36:39]
	v_mfma_f32_16x16x32_bf16 v[16:19], v[128:131], v[196:199], v[16:19]
	v_mfma_f32_16x16x32_bf16 v[20:23], v[136:139], v[196:199], v[20:23]
	v_mfma_f32_16x16x32_bf16 v[0:3], v[128:131], v[204:207], v[0:3]
	v_mfma_f32_16x16x32_bf16 v[4:7], v[136:139], v[204:207], v[4:7]
	v_mfma_f32_16x16x32_bf16 v[48:51], v[132:135], v[184:187], v[48:51]
	v_mfma_f32_16x16x32_bf16 v[52:55], v[140:143], v[184:187], v[52:55]
	v_mfma_f32_16x16x32_bf16 v[32:35], v[132:135], v[192:195], v[32:35]
	v_mfma_f32_16x16x32_bf16 v[36:39], v[140:143], v[192:195], v[36:39]
	v_mfma_f32_16x16x32_bf16 v[16:19], v[132:135], v[200:203], v[16:19]
	v_mfma_f32_16x16x32_bf16 v[20:23], v[140:143], v[200:203], v[20:23]
	v_mfma_f32_16x16x32_bf16 v[0:3], v[132:135], v[208:211], v[0:3]
	v_mfma_f32_16x16x32_bf16 v[4:7], v[140:143], v[208:211], v[4:7]
	s_setprio 0
	s_setprio 1
	v_mfma_f32_16x16x32_bf16 v[56:59], v[158:161], v[180:183], v[56:59]
	v_mfma_f32_16x16x32_bf16 v[60:63], v[172:175], v[180:183], v[60:63]
	v_mfma_f32_16x16x32_bf16 v[40:43], v[158:161], v[188:191], v[40:43]
	v_mfma_f32_16x16x32_bf16 v[44:47], v[172:175], v[188:191], v[44:47]
	v_mfma_f32_16x16x32_bf16 v[24:27], v[158:161], v[196:199], v[24:27]
	v_mfma_f32_16x16x32_bf16 v[28:31], v[172:175], v[196:199], v[28:31]
	v_mfma_f32_16x16x32_bf16 v[8:11], v[158:161], v[204:207], v[8:11]
	v_mfma_f32_16x16x32_bf16 v[12:15], v[172:175], v[204:207], v[12:15]
	v_mfma_f32_16x16x32_bf16 v[56:59], v[162:165], v[184:187], v[56:59]
	v_mfma_f32_16x16x32_bf16 v[60:63], v[176:179], v[184:187], v[60:63]
	v_mfma_f32_16x16x32_bf16 v[40:43], v[162:165], v[192:195], v[40:43]
	v_mfma_f32_16x16x32_bf16 v[44:47], v[176:179], v[192:195], v[44:47]
	v_mfma_f32_16x16x32_bf16 v[24:27], v[162:165], v[200:203], v[24:27]
	v_mfma_f32_16x16x32_bf16 v[28:31], v[176:179], v[200:203], v[28:31]
	v_mfma_f32_16x16x32_bf16 v[8:11], v[162:165], v[208:211], v[8:11]
	v_mfma_f32_16x16x32_bf16 v[12:15], v[176:179], v[208:211], v[12:15]
	s_barrier
	s_setprio 0
	s_add_i32 s36, s36, 2
	s_add_u32 s34, s34, 0x100
	s_addc_u32 s35, s35, 0
	s_add_u32 s22, s22, 0x100
	s_addc_u32 s23, s23, 0
	s_cmp_gt_u32 s36, 5
	s_cbranch_scc1 .Lpeel_done_1

.Lpeel_done_1:
	v_readlane_b32 s22, v254, 27
	v_readlane_b32 s23, v254, 28
	s_and_b64 vcc, exec, s[22:23]
	s_cbranch_vccz .LBB0_1696
	s_barrier

.LBB0_2019:
	s_cmp_lt_u32 s5, 0x3fffffff
	s_cselect_b64 s[40:41], -1, 0
	s_ashr_i32 s23, s22, 31
	s_and_b64 s[40:41], s[36:37], s[40:41]
	s_lshl_b64 s[36:37], s[22:23], 21
	s_add_u32 s5, s86, s36
	s_addc_u32 s21, s87, s37
	s_add_u32 s36, s5, s38
	s_addc_u32 s37, s21, s39
	s_and_b64 s[48:49], s[40:41], exec
	s_cselect_b32 s5, s37, s47
	s_cselect_b32 s23, s36, s46
	s_ashr_i32 s21, s20, 31
	s_lshl_b64 s[48:49], s[20:21], 21
	v_readlane_b32 s68, v254, 13
	v_readlane_b32 s69, v254, 14
	s_add_u32 s21, s68, s48
	s_addc_u32 s43, s69, s49
	s_add_u32 s38, s21, s38
	s_addc_u32 s39, s43, s39
	s_and_b64 s[48:49], s[40:41], exec
	s_cselect_b32 s21, s39, s45
	s_cselect_b32 s43, s38, s44
	s_add_i32 s68, s67, -2
	s_add_u32 s69, s44, 0x100
	s_addc_u32 s70, s45, 0
	s_add_u32 s44, s46, 0x100080
	s_addc_u32 s45, s47, 0
	s_mov_b32 s46, 0
	s_waitcnt vmcnt(0)
	ds_read_b128 v[128:131], v244
	ds_read_b128 v[132:135], v244 offset:1024
	ds_read_b128 v[136:139], v244 offset:2048
	ds_read_b128 v[140:143], v244 offset:3072
	ds_read_b128 v[144:147], v245
	ds_read_b128 v[148:151], v245 offset:1024
	ds_read_b128 v[152:155], v245 offset:2048
	ds_read_b128 v[156:159], v245 offset:3072
	s_add_i32 s71, s46, 2
	s_add_u32 s47, s44, 0xfff00080
	s_addc_u32 s48, s45, -1
	s_cmp_eq_u32 s68, s46
	s_cselect_b32 s46, s43, s69
	s_cselect_b32 s49, s5, s48
	s_cselect_b32 s48, s23, s47
	s_cselect_b32 s47, s21, s70
	v_lshl_add_u64 v[192:193], s[44:45], 0, v[218:219]
	s_add_i32 m0, s94, 0xc000
	ds_read_b128 v[160:163], v246
	ds_read_b128 v[164:167], v246 offset:1024
	ds_read_b128 v[168:171], v246 offset:2048
	ds_read_b128 v[172:175], v246 offset:3072
	ds_read_b128 v[176:179], v246 offset:4096
	ds_read_b128 v[180:183], v246 offset:5120
	ds_read_b128 v[184:187], v246 offset:6144
	ds_read_b128 v[188:191], v246 offset:7168
	global_load_lds_dwordx4 v[192:193], off
	v_lshl_add_u64 v[192:193], s[44:45], 0, v[220:221]
	s_add_i32 m0, s94, 0xe000
	s_nop 0
	global_load_lds_dwordx4 v[192:193], off
	s_waitcnt vmcnt(8)
	s_waitcnt lgkmcnt(0)
	s_setprio 1
	s_barrier
	v_mfma_f32_16x16x32_bf16 v[112:115], v[128:131], v[160:163], 0
	v_mfma_f32_16x16x32_bf16 v[116:119], v[136:139], v[160:163], 0
	v_mfma_f32_16x16x32_bf16 v[100:103], v[128:131], v[168:171], 0
	v_mfma_f32_16x16x32_bf16 v[96:99], v[136:139], v[168:171], 0
	v_mfma_f32_16x16x32_bf16 v[84:87], v[128:131], v[176:179], 0
	v_mfma_f32_16x16x32_bf16 v[80:83], v[136:139], v[176:179], 0
	v_mfma_f32_16x16x32_bf16 v[52:55], v[128:131], v[184:187], 0
	v_mfma_f32_16x16x32_bf16 v[48:51], v[136:139], v[184:187], 0
	v_mfma_f32_16x16x32_bf16 v[112:115], v[132:135], v[164:167], v[112:115]
	v_mfma_f32_16x16x32_bf16 v[116:119], v[140:143], v[164:167], v[116:119]
	v_mfma_f32_16x16x32_bf16 v[100:103], v[132:135], v[172:175], v[100:103]
	v_mfma_f32_16x16x32_bf16 v[96:99], v[140:143], v[172:175], v[96:99]
	v_mfma_f32_16x16x32_bf16 v[84:87], v[132:135], v[180:183], v[84:87]
	v_mfma_f32_16x16x32_bf16 v[80:83], v[140:143], v[180:183], v[80:83]
	v_mfma_f32_16x16x32_bf16 v[52:55], v[132:135], v[188:191], v[52:55]
	v_mfma_f32_16x16x32_bf16 v[48:51], v[140:143], v[188:191], v[48:51]
	s_setprio 0
	s_setprio 1
	v_mfma_f32_16x16x32_bf16 v[124:127], v[144:147], v[160:163], 0
	v_mfma_f32_16x16x32_bf16 v[120:123], v[152:155], v[160:163], 0
	v_mfma_f32_16x16x32_bf16 v[108:111], v[144:147], v[168:171], 0
	v_mfma_f32_16x16x32_bf16 v[104:107], v[152:155], v[168:171], 0
	v_mfma_f32_16x16x32_bf16 v[92:95], v[144:147], v[176:179], 0
	v_mfma_f32_16x16x32_bf16 v[88:91], v[152:155], v[176:179], 0
	v_mfma_f32_16x16x32_bf16 v[68:71], v[144:147], v[184:187], 0
	v_mfma_f32_16x16x32_bf16 v[64:67], v[152:155], v[184:187], 0
	v_mfma_f32_16x16x32_bf16 v[124:127], v[148:151], v[164:167], v[124:127]
	v_mfma_f32_16x16x32_bf16 v[120:123], v[156:159], v[164:167], v[120:123]
	v_mfma_f32_16x16x32_bf16 v[108:111], v[148:151], v[172:175], v[108:111]
	v_mfma_f32_16x16x32_bf16 v[104:107], v[156:159], v[172:175], v[104:107]
	v_mfma_f32_16x16x32_bf16 v[92:95], v[148:151], v[180:183], v[92:95]
	v_mfma_f32_16x16x32_bf16 v[88:91], v[156:159], v[180:183], v[88:91]
	v_mfma_f32_16x16x32_bf16 v[68:71], v[148:151], v[188:191], v[68:71]
	v_mfma_f32_16x16x32_bf16 v[64:67], v[156:159], v[188:191], v[64:67]
	s_barrier
	s_setprio 0
	s_add_i32 s76, s60, s97
	v_lshl_add_u64 v[192:193], s[46:47], 0, v[210:211]
	s_mov_b32 m0, s76
	ds_read_b128 v[160:163], v246 offset:16384
	ds_read_b128 v[164:167], v246 offset:17408
	ds_read_b128 v[168:171], v246 offset:18432
	ds_read_b128 v[172:175], v246 offset:19456
	ds_read_b128 v[176:179], v246 offset:20480
	ds_read_b128 v[180:183], v246 offset:21504
	ds_read_b128 v[184:187], v246 offset:22528
	ds_read_b128 v[188:191], v246 offset:23552
	global_load_lds_dwordx4 v[192:193], off
	s_add_i32 m0, s76, 0x2000
	s_add_u32 s76, s46, 0x100000
	v_lshl_add_u64 v[194:195], s[46:47], 0, v[214:215]
	s_addc_u32 s77, s47, 0
	s_add_i32 s78, s61, s97
	global_load_lds_dwordx4 v[194:195], off
	v_lshl_add_u64 v[196:197], s[76:77], 0, v[210:211]
	s_mov_b32 m0, s78
	v_lshl_add_u64 v[198:199], s[48:49], 0, v[212:213]
	global_load_lds_dwordx4 v[196:197], off
	v_lshl_add_u64 v[196:197], s[76:77], 0, v[214:215]
	s_add_i32 m0, s78, 0x2000
	s_nop 0
	global_load_lds_dwordx4 v[196:197], off
	v_lshl_add_u64 v[196:197], s[48:49], 0, v[208:209]
	s_mov_b32 m0, s94
	s_nop 0
	global_load_lds_dwordx4 v[196:197], off
	s_mov_b32 m0, s2
	s_nop 0
	global_load_lds_dwordx4 v[198:199], off
	s_waitcnt vmcnt(8)
	s_waitcnt lgkmcnt(0)
	s_setprio 1
	s_barrier
	v_mfma_f32_16x16x32_bf16 v[60:63], v[128:131], v[160:163], 0
	v_mfma_f32_16x16x32_bf16 v[56:59], v[136:139], v[160:163], 0
	v_mfma_f32_16x16x32_bf16 v[36:39], v[128:131], v[168:171], 0
	v_mfma_f32_16x16x32_bf16 v[32:35], v[136:139], v[168:171], 0
	v_mfma_f32_16x16x32_bf16 v[20:23], v[128:131], v[176:179], 0
	v_mfma_f32_16x16x32_bf16 v[16:19], v[136:139], v[176:179], 0
	v_mfma_f32_16x16x32_bf16 v[4:7], v[128:131], v[184:187], 0
	v_mfma_f32_16x16x32_bf16 v[0:3], v[136:139], v[184:187], 0
	v_mfma_f32_16x16x32_bf16 v[60:63], v[132:135], v[164:167], v[60:63]
	v_mfma_f32_16x16x32_bf16 v[56:59], v[140:143], v[164:167], v[56:59]
	v_mfma_f32_16x16x32_bf16 v[36:39], v[132:135], v[172:175], v[36:39]
	v_mfma_f32_16x16x32_bf16 v[32:35], v[140:143], v[172:175], v[32:35]
	v_mfma_f32_16x16x32_bf16 v[20:23], v[132:135], v[180:183], v[20:23]
	v_mfma_f32_16x16x32_bf16 v[16:19], v[140:143], v[180:183], v[16:19]
	v_mfma_f32_16x16x32_bf16 v[4:7], v[132:135], v[188:191], v[4:7]
	v_mfma_f32_16x16x32_bf16 v[0:3], v[140:143], v[188:191], v[0:3]
	s_setprio 0
	s_setprio 1
	v_mfma_f32_16x16x32_bf16 v[76:79], v[144:147], v[160:163], 0
	v_mfma_f32_16x16x32_bf16 v[72:75], v[152:155], v[160:163], 0
	v_mfma_f32_16x16x32_bf16 v[44:47], v[144:147], v[168:171], 0
	v_mfma_f32_16x16x32_bf16 v[40:43], v[152:155], v[168:171], 0
	v_mfma_f32_16x16x32_bf16 v[28:31], v[144:147], v[176:179], 0
	v_mfma_f32_16x16x32_bf16 v[24:27], v[152:155], v[176:179], 0
	v_mfma_f32_16x16x32_bf16 v[12:15], v[144:147], v[184:187], 0
	v_mfma_f32_16x16x32_bf16 v[8:11], v[152:155], v[184:187], 0
	v_mfma_f32_16x16x32_bf16 v[76:79], v[148:151], v[164:167], v[76:79]
	v_mfma_f32_16x16x32_bf16 v[72:75], v[156:159], v[164:167], v[72:75]
	v_mfma_f32_16x16x32_bf16 v[44:47], v[148:151], v[172:175], v[44:47]
	v_mfma_f32_16x16x32_bf16 v[40:43], v[156:159], v[172:175], v[40:43]
	v_mfma_f32_16x16x32_bf16 v[28:31], v[148:151], v[180:183], v[28:31]
	v_mfma_f32_16x16x32_bf16 v[24:27], v[156:159], v[180:183], v[24:27]
	v_mfma_f32_16x16x32_bf16 v[12:15], v[148:151], v[188:191], v[12:15]
	v_mfma_f32_16x16x32_bf16 v[8:11], v[156:159], v[188:191], v[8:11]
	s_barrier
	s_setprio 0
	s_add_i32 s76, 0, 0x18000
	s_add_i32 s77, 0, 0x1c000
	v_add_u32_e32 v140, s76, v243
	v_add_u32_e32 v156, s77, v243
	ds_read_b128 v[128:131], v140
	ds_read_b128 v[132:135], v140 offset:1024
	ds_read_b128 v[136:139], v140 offset:2048
	ds_read_b128 v[140:143], v140 offset:3072
	ds_read_b128 v[144:147], v156
	ds_read_b128 v[148:151], v156 offset:1024
	ds_read_b128 v[152:155], v156 offset:2048
	ds_read_b128 v[156:159], v156 offset:3072
	s_add_u32 s48, s48, 0x100000
	s_addc_u32 s49, s49, 0
	s_mov_b32 m0, s3
	v_lshl_add_u64 v[200:201], s[48:49], 0, v[208:209]
	ds_read_b128 v[160:163], v246 offset:32768
	ds_read_b128 v[164:167], v246 offset:33792
	ds_read_b128 v[168:171], v246 offset:34816
	ds_read_b128 v[172:175], v246 offset:35840
	ds_read_b128 v[176:179], v246 offset:36864
	ds_read_b128 v[180:183], v246 offset:37888
	ds_read_b128 v[184:187], v246 offset:38912
	ds_read_b128 v[188:191], v246 offset:39936
	global_load_lds_dwordx4 v[200:201], off
	v_lshl_add_u64 v[200:201], s[48:49], 0, v[212:213]
	s_mov_b32 m0, s33
	s_nop 0
	global_load_lds_dwordx4 v[200:201], off
	s_waitcnt vmcnt(8)
	s_waitcnt lgkmcnt(0)
	s_setprio 1
	s_barrier
	v_mfma_f32_16x16x32_bf16 v[112:115], v[128:131], v[160:163], v[112:115]
	v_mfma_f32_16x16x32_bf16 v[116:119], v[136:139], v[160:163], v[116:119]
	v_mfma_f32_16x16x32_bf16 v[100:103], v[128:131], v[168:171], v[100:103]
	v_mfma_f32_16x16x32_bf16 v[96:99], v[136:139], v[168:171], v[96:99]
	v_mfma_f32_16x16x32_bf16 v[84:87], v[128:131], v[176:179], v[84:87]
	v_mfma_f32_16x16x32_bf16 v[80:83], v[136:139], v[176:179], v[80:83]
	v_mfma_f32_16x16x32_bf16 v[52:55], v[128:131], v[184:187], v[52:55]
	v_mfma_f32_16x16x32_bf16 v[48:51], v[136:139], v[184:187], v[48:51]
	v_mfma_f32_16x16x32_bf16 v[112:115], v[132:135], v[164:167], v[112:115]
	v_mfma_f32_16x16x32_bf16 v[116:119], v[140:143], v[164:167], v[116:119]
	v_mfma_f32_16x16x32_bf16 v[100:103], v[132:135], v[172:175], v[100:103]
	v_mfma_f32_16x16x32_bf16 v[96:99], v[140:143], v[172:175], v[96:99]
	v_mfma_f32_16x16x32_bf16 v[84:87], v[132:135], v[180:183], v[84:87]
	v_mfma_f32_16x16x32_bf16 v[80:83], v[140:143], v[180:183], v[80:83]
	v_mfma_f32_16x16x32_bf16 v[52:55], v[132:135], v[188:191], v[52:55]
	v_mfma_f32_16x16x32_bf16 v[48:51], v[140:143], v[188:191], v[48:51]
	s_setprio 0
	s_setprio 1
	v_mfma_f32_16x16x32_bf16 v[124:127], v[144:147], v[160:163], v[124:127]
	v_mfma_f32_16x16x32_bf16 v[120:123], v[152:155], v[160:163], v[120:123]
	v_mfma_f32_16x16x32_bf16 v[108:111], v[144:147], v[168:171], v[108:111]
	v_mfma_f32_16x16x32_bf16 v[104:107], v[152:155], v[168:171], v[104:107]
	v_mfma_f32_16x16x32_bf16 v[92:95], v[144:147], v[176:179], v[92:95]
	v_mfma_f32_16x16x32_bf16 v[88:91], v[152:155], v[176:179], v[88:91]
	v_mfma_f32_16x16x32_bf16 v[68:71], v[144:147], v[184:187], v[68:71]
	v_mfma_f32_16x16x32_bf16 v[64:67], v[152:155], v[184:187], v[64:67]
	v_mfma_f32_16x16x32_bf16 v[124:127], v[148:151], v[164:167], v[124:127]
	v_mfma_f32_16x16x32_bf16 v[120:123], v[156:159], v[164:167], v[120:123]
	v_mfma_f32_16x16x32_bf16 v[108:111], v[148:151], v[172:175], v[108:111]
	v_mfma_f32_16x16x32_bf16 v[104:107], v[156:159], v[172:175], v[104:107]
	v_mfma_f32_16x16x32_bf16 v[92:95], v[148:151], v[180:183], v[92:95]
	v_mfma_f32_16x16x32_bf16 v[88:91], v[156:159], v[180:183], v[88:91]
	v_mfma_f32_16x16x32_bf16 v[68:71], v[148:151], v[188:191], v[68:71]
	v_mfma_f32_16x16x32_bf16 v[64:67], v[156:159], v[188:191], v[64:67]
	s_barrier
	s_setprio 0
	s_add_i32 s48, s76, s97
	v_lshl_add_u64 v[192:193], v[192:193], 0, s[16:17]
	s_mov_b32 m0, s48
	ds_read_b128 v[160:163], v246 offset:49152
	ds_read_b128 v[164:167], v246 offset:50176
	ds_read_b128 v[168:171], v246 offset:51200
	ds_read_b128 v[172:175], v246 offset:52224
	ds_read_b128 v[176:179], v246 offset:53248
	ds_read_b128 v[180:183], v246 offset:54272
	ds_read_b128 v[184:187], v246 offset:55296
	ds_read_b128 v[188:191], v246 offset:56320
	global_load_lds_dwordx4 v[192:193], off
	s_add_i32 m0, s48, 0x2000
	s_add_u32 s46, s46, 0x100080
	v_lshl_add_u64 v[192:193], v[194:195], 0, s[16:17]
	s_addc_u32 s47, s47, 0
	s_add_i32 s48, s77, s97
	global_load_lds_dwordx4 v[192:193], off
	v_lshl_add_u64 v[192:193], s[46:47], 0, v[210:211]
	s_mov_b32 m0, s48
	s_nop 0
	global_load_lds_dwordx4 v[192:193], off
	v_lshl_add_u64 v[192:193], s[46:47], 0, v[214:215]
	s_add_i32 m0, s48, 0x2000
	s_nop 0
	global_load_lds_dwordx4 v[192:193], off
	v_lshl_add_u64 v[192:193], v[196:197], 0, s[16:17]
	s_mov_b32 m0, s54
	s_nop 0
	global_load_lds_dwordx4 v[192:193], off
	v_lshl_add_u64 v[192:193], v[198:199], 0, s[16:17]
	s_mov_b32 m0, s55
	s_nop 0
	global_load_lds_dwordx4 v[192:193], off
	s_waitcnt vmcnt(8)
	s_waitcnt lgkmcnt(0)
	s_setprio 1
	s_barrier
	v_mfma_f32_16x16x32_bf16 v[60:63], v[128:131], v[160:163], v[60:63]
	v_mfma_f32_16x16x32_bf16 v[56:59], v[136:139], v[160:163], v[56:59]
	v_mfma_f32_16x16x32_bf16 v[36:39], v[128:131], v[168:171], v[36:39]
	v_mfma_f32_16x16x32_bf16 v[32:35], v[136:139], v[168:171], v[32:35]
	v_mfma_f32_16x16x32_bf16 v[20:23], v[128:131], v[176:179], v[20:23]
	v_mfma_f32_16x16x32_bf16 v[16:19], v[136:139], v[176:179], v[16:19]
	v_mfma_f32_16x16x32_bf16 v[4:7], v[128:131], v[184:187], v[4:7]
	v_mfma_f32_16x16x32_bf16 v[0:3], v[136:139], v[184:187], v[0:3]
	v_mfma_f32_16x16x32_bf16 v[60:63], v[132:135], v[164:167], v[60:63]
	v_mfma_f32_16x16x32_bf16 v[56:59], v[140:143], v[164:167], v[56:59]
	v_mfma_f32_16x16x32_bf16 v[36:39], v[132:135], v[172:175], v[36:39]
	v_mfma_f32_16x16x32_bf16 v[32:35], v[140:143], v[172:175], v[32:35]
	v_mfma_f32_16x16x32_bf16 v[20:23], v[132:135], v[180:183], v[20:23]
	v_mfma_f32_16x16x32_bf16 v[16:19], v[140:143], v[180:183], v[16:19]
	v_mfma_f32_16x16x32_bf16 v[4:7], v[132:135], v[188:191], v[4:7]
	v_mfma_f32_16x16x32_bf16 v[0:3], v[140:143], v[188:191], v[0:3]
	s_setprio 0
	s_setprio 1
	v_mfma_f32_16x16x32_bf16 v[76:79], v[144:147], v[160:163], v[76:79]
	v_mfma_f32_16x16x32_bf16 v[72:75], v[152:155], v[160:163], v[72:75]
	v_mfma_f32_16x16x32_bf16 v[44:47], v[144:147], v[168:171], v[44:47]
	v_mfma_f32_16x16x32_bf16 v[40:43], v[152:155], v[168:171], v[40:43]
	v_mfma_f32_16x16x32_bf16 v[28:31], v[144:147], v[176:179], v[28:31]
	v_mfma_f32_16x16x32_bf16 v[24:27], v[152:155], v[176:179], v[24:27]
	v_mfma_f32_16x16x32_bf16 v[12:15], v[144:147], v[184:187], v[12:15]
	v_mfma_f32_16x16x32_bf16 v[8:11], v[152:155], v[184:187], v[8:11]
	v_mfma_f32_16x16x32_bf16 v[76:79], v[148:151], v[164:167], v[76:79]
	v_mfma_f32_16x16x32_bf16 v[72:75], v[156:159], v[164:167], v[72:75]
	v_mfma_f32_16x16x32_bf16 v[44:47], v[148:151], v[172:175], v[44:47]
	v_mfma_f32_16x16x32_bf16 v[40:43], v[156:159], v[172:175], v[40:43]
	v_mfma_f32_16x16x32_bf16 v[28:31], v[148:151], v[180:183], v[28:31]
	v_mfma_f32_16x16x32_bf16 v[24:27], v[156:159], v[180:183], v[24:27]
	v_mfma_f32_16x16x32_bf16 v[12:15], v[148:151], v[188:191], v[12:15]
	v_mfma_f32_16x16x32_bf16 v[8:11], v[156:159], v[188:191], v[8:11]
	s_barrier
	s_setprio 0
	s_add_u32 s69, s69, 0x100
	s_addc_u32 s70, s70, 0
	s_add_u32 s44, s44, 0x100
	s_addc_u32 s45, s45, 0
	s_cmp_ge_u32 s71, s67
	s_mov_b32 s46, s71
	s_cbranch_scc1 .Lpeel_done_2

.Lpeel_done_2:
	v_readlane_b32 s44, v254, 27
	v_readlane_b32 s45, v254, 28
	s_and_b64 vcc, exec, s[44:45]
	s_cbranch_vccz .LBB0_2028
	s_barrier
	s_cmp_lt_i32 s14, 0
	s_mov_b64 s[44:45], -1
	s_cbranch_scc1 .LBB0_2029

.LBB0_2288:
	s_ashr_i32 s25, s24, 31
	s_lshl_b64 s[86:87], s[24:25], 21
	v_readlane_b32 s88, v254, 52
	v_readlane_b32 s89, v254, 53
	s_add_u32 s5, s88, s86
	s_addc_u32 s25, s89, s87
	s_add_u32 s38, s5, s38
	s_addc_u32 s39, s25, s39
	s_and_b64 s[48:49], s[48:49], exec
	s_cselect_b32 s5, s39, s45
	s_cselect_b32 s25, s38, s44
	s_add_i32 s43, s84, -2
	s_add_u32 s85, s44, 0x100
	s_addc_u32 s86, s45, 0
	s_add_u32 s44, s46, 0x100080
	s_addc_u32 s45, s47, 0
	s_mov_b32 s46, 0
	ds_read_b128 v[148:151], v159
	ds_read_b128 v[164:167], v159 offset:1024
	ds_read_b128 v[168:171], v159 offset:2048
	ds_read_b128 v[172:175], v159 offset:3072
	ds_read_b128 v[176:179], v160
	ds_read_b128 v[180:183], v160 offset:1024
	ds_read_b128 v[184:187], v160 offset:2048
	ds_read_b128 v[188:191], v160 offset:3072
	s_add_i32 s87, s46, 2
	s_add_u32 s47, s44, 0xfff00080
	s_addc_u32 s48, s45, -1
	s_cmp_eq_u32 s43, s46
	s_cselect_b32 s46, s25, s85
	s_cselect_b32 s49, s37, s48
	s_cselect_b32 s48, s36, s47
	s_cselect_b32 s47, s5, s86
	v_lshl_add_u64 v[152:153], s[44:45], 0, v[142:143]
	s_add_i32 m0, s94, 0xc000
	ds_read_b128 v[192:195], v161
	ds_read_b128 v[196:199], v161 offset:1024
	ds_read_b128 v[200:203], v161 offset:2048
	ds_read_b128 v[204:207], v161 offset:3072
	ds_read_b128 v[208:211], v161 offset:4096
	ds_read_b128 v[212:215], v161 offset:5120
	ds_read_b128 v[216:219], v161 offset:6144
	ds_read_b128 v[220:223], v161 offset:7168
	global_load_lds_dwordx4 v[152:153], off
	v_lshl_add_u64 v[152:153], s[44:45], 0, v[144:145]
	s_add_i32 m0, s94, 0xe000
	s_nop 0
	global_load_lds_dwordx4 v[152:153], off
	s_waitcnt vmcnt(8)
	s_waitcnt lgkmcnt(0)
	s_setprio 1
	s_barrier
	v_mfma_f32_16x16x32_bf16 v[112:115], v[148:151], v[192:195], 0
	v_mfma_f32_16x16x32_bf16 v[116:119], v[168:171], v[192:195], 0
	v_mfma_f32_16x16x32_bf16 v[100:103], v[148:151], v[200:203], 0
	v_mfma_f32_16x16x32_bf16 v[96:99], v[168:171], v[200:203], 0
	v_mfma_f32_16x16x32_bf16 v[84:87], v[148:151], v[208:211], 0
	v_mfma_f32_16x16x32_bf16 v[80:83], v[168:171], v[208:211], 0
	v_mfma_f32_16x16x32_bf16 v[52:55], v[148:151], v[216:219], 0
	v_mfma_f32_16x16x32_bf16 v[48:51], v[168:171], v[216:219], 0
	v_mfma_f32_16x16x32_bf16 v[112:115], v[164:167], v[196:199], v[112:115]
	v_mfma_f32_16x16x32_bf16 v[116:119], v[172:175], v[196:199], v[116:119]
	v_mfma_f32_16x16x32_bf16 v[100:103], v[164:167], v[204:207], v[100:103]
	v_mfma_f32_16x16x32_bf16 v[96:99], v[172:175], v[204:207], v[96:99]
	v_mfma_f32_16x16x32_bf16 v[84:87], v[164:167], v[212:215], v[84:87]
	v_mfma_f32_16x16x32_bf16 v[80:83], v[172:175], v[212:215], v[80:83]
	v_mfma_f32_16x16x32_bf16 v[52:55], v[164:167], v[220:223], v[52:55]
	v_mfma_f32_16x16x32_bf16 v[48:51], v[172:175], v[220:223], v[48:51]
	s_setprio 0
	s_setprio 1
	v_mfma_f32_16x16x32_bf16 v[124:127], v[176:179], v[192:195], 0
	v_mfma_f32_16x16x32_bf16 v[120:123], v[184:187], v[192:195], 0
	v_mfma_f32_16x16x32_bf16 v[108:111], v[176:179], v[200:203], 0
	v_mfma_f32_16x16x32_bf16 v[104:107], v[184:187], v[200:203], 0
	v_mfma_f32_16x16x32_bf16 v[92:95], v[176:179], v[208:211], 0
	v_mfma_f32_16x16x32_bf16 v[88:91], v[184:187], v[208:211], 0
	v_mfma_f32_16x16x32_bf16 v[68:71], v[176:179], v[216:219], 0
	v_mfma_f32_16x16x32_bf16 v[64:67], v[184:187], v[216:219], 0
	v_mfma_f32_16x16x32_bf16 v[124:127], v[180:183], v[196:199], v[124:127]
	v_mfma_f32_16x16x32_bf16 v[120:123], v[188:191], v[196:199], v[120:123]
	v_mfma_f32_16x16x32_bf16 v[108:111], v[180:183], v[204:207], v[108:111]
	v_mfma_f32_16x16x32_bf16 v[104:107], v[188:191], v[204:207], v[104:107]
	v_mfma_f32_16x16x32_bf16 v[92:95], v[180:183], v[212:215], v[92:95]
	v_mfma_f32_16x16x32_bf16 v[88:91], v[188:191], v[212:215], v[88:91]
	v_mfma_f32_16x16x32_bf16 v[68:71], v[180:183], v[220:223], v[68:71]
	v_mfma_f32_16x16x32_bf16 v[64:67], v[188:191], v[220:223], v[64:67]
	s_barrier
	s_setprio 0
	s_add_i32 s88, s77, s97
	v_lshl_add_u64 v[152:153], s[46:47], 0, v[132:133]
	s_mov_b32 m0, s88
	ds_read_b128 v[192:195], v161 offset:16384
	ds_read_b128 v[196:199], v161 offset:17408
	ds_read_b128 v[200:203], v161 offset:18432
	ds_read_b128 v[204:207], v161 offset:19456
	ds_read_b128 v[208:211], v161 offset:20480
	ds_read_b128 v[212:215], v161 offset:21504
	ds_read_b128 v[216:219], v161 offset:22528
	ds_read_b128 v[220:223], v161 offset:23552
	global_load_lds_dwordx4 v[152:153], off
	s_add_i32 m0, s88, 0x2000
	s_add_u32 s88, s46, 0x100000
	v_lshl_add_u64 v[224:225], s[46:47], 0, v[136:137]
	s_addc_u32 s89, s47, 0
	s_add_i32 s90, s78, s97
	global_load_lds_dwordx4 v[224:225], off
	v_lshl_add_u64 v[226:227], s[88:89], 0, v[132:133]
	s_mov_b32 m0, s90
	v_lshl_add_u64 v[228:229], s[48:49], 0, v[134:135]
	global_load_lds_dwordx4 v[226:227], off
	v_lshl_add_u64 v[226:227], s[88:89], 0, v[136:137]
	s_add_i32 m0, s90, 0x2000
	s_nop 0
	global_load_lds_dwordx4 v[226:227], off
	v_lshl_add_u64 v[226:227], s[48:49], 0, v[130:131]
	s_mov_b32 m0, s94
	s_nop 0
	global_load_lds_dwordx4 v[226:227], off
	s_mov_b32 m0, s52
	s_nop 0
	global_load_lds_dwordx4 v[228:229], off
	s_waitcnt vmcnt(8)
	s_waitcnt lgkmcnt(0)
	s_setprio 1
	s_barrier
	v_mfma_f32_16x16x32_bf16 v[60:63], v[148:151], v[192:195], 0
	v_mfma_f32_16x16x32_bf16 v[56:59], v[168:171], v[192:195], 0
	v_mfma_f32_16x16x32_bf16 v[36:39], v[148:151], v[200:203], 0
	v_mfma_f32_16x16x32_bf16 v[32:35], v[168:171], v[200:203], 0
	v_mfma_f32_16x16x32_bf16 v[20:23], v[148:151], v[208:211], 0
	v_mfma_f32_16x16x32_bf16 v[16:19], v[168:171], v[208:211], 0
	v_mfma_f32_16x16x32_bf16 v[4:7], v[148:151], v[216:219], 0
	v_mfma_f32_16x16x32_bf16 v[0:3], v[168:171], v[216:219], 0
	v_mfma_f32_16x16x32_bf16 v[60:63], v[164:167], v[196:199], v[60:63]
	v_mfma_f32_16x16x32_bf16 v[56:59], v[172:175], v[196:199], v[56:59]
	v_mfma_f32_16x16x32_bf16 v[36:39], v[164:167], v[204:207], v[36:39]
	v_mfma_f32_16x16x32_bf16 v[32:35], v[172:175], v[204:207], v[32:35]
	v_mfma_f32_16x16x32_bf16 v[20:23], v[164:167], v[212:215], v[20:23]
	v_mfma_f32_16x16x32_bf16 v[16:19], v[172:175], v[212:215], v[16:19]
	v_mfma_f32_16x16x32_bf16 v[4:7], v[164:167], v[220:223], v[4:7]
	v_mfma_f32_16x16x32_bf16 v[0:3], v[172:175], v[220:223], v[0:3]
	s_setprio 0
	s_setprio 1
	v_mfma_f32_16x16x32_bf16 v[76:79], v[176:179], v[192:195], 0
	v_mfma_f32_16x16x32_bf16 v[72:75], v[184:187], v[192:195], 0
	v_mfma_f32_16x16x32_bf16 v[44:47], v[176:179], v[200:203], 0
	v_mfma_f32_16x16x32_bf16 v[40:43], v[184:187], v[200:203], 0
	v_mfma_f32_16x16x32_bf16 v[28:31], v[176:179], v[208:211], 0
	v_mfma_f32_16x16x32_bf16 v[24:27], v[184:187], v[208:211], 0
	v_mfma_f32_16x16x32_bf16 v[12:15], v[176:179], v[216:219], 0
	v_mfma_f32_16x16x32_bf16 v[8:11], v[184:187], v[216:219], 0
	v_mfma_f32_16x16x32_bf16 v[76:79], v[180:183], v[196:199], v[76:79]
	v_mfma_f32_16x16x32_bf16 v[72:75], v[188:191], v[196:199], v[72:75]
	v_mfma_f32_16x16x32_bf16 v[44:47], v[180:183], v[204:207], v[44:47]
	v_mfma_f32_16x16x32_bf16 v[40:43], v[188:191], v[204:207], v[40:43]
	v_mfma_f32_16x16x32_bf16 v[28:31], v[180:183], v[212:215], v[28:31]
	v_mfma_f32_16x16x32_bf16 v[24:27], v[188:191], v[212:215], v[24:27]
	v_mfma_f32_16x16x32_bf16 v[12:15], v[180:183], v[220:223], v[12:15]
	v_mfma_f32_16x16x32_bf16 v[8:11], v[188:191], v[220:223], v[8:11]
	s_barrier
	s_setprio 0
	s_add_i32 s88, 0, 0x18000
	v_add_u32_e32 v163, s88, v157
	s_add_i32 s89, 0, 0x1c000
	ds_read_b128 v[148:151], v163
	ds_read_b128 v[164:167], v163 offset:1024
	ds_read_b128 v[168:171], v163 offset:2048
	ds_read_b128 v[172:175], v163 offset:3072
	v_add_u32_e32 v163, s89, v157
	ds_read_b128 v[176:179], v163
	ds_read_b128 v[180:183], v163 offset:1024
	ds_read_b128 v[184:187], v163 offset:2048
	ds_read_b128 v[188:191], v163 offset:3072
	s_add_u32 s48, s48, 0x100000
	s_addc_u32 s49, s49, 0
	s_mov_b32 m0, s53
	v_lshl_add_u64 v[230:231], s[48:49], 0, v[130:131]
	ds_read_b128 v[192:195], v161 offset:32768
	ds_read_b128 v[196:199], v161 offset:33792
	ds_read_b128 v[200:203], v161 offset:34816
	ds_read_b128 v[204:207], v161 offset:35840
	ds_read_b128 v[208:211], v161 offset:36864
	ds_read_b128 v[212:215], v161 offset:37888
	ds_read_b128 v[216:219], v161 offset:38912
	ds_read_b128 v[220:223], v161 offset:39936
	global_load_lds_dwordx4 v[230:231], off
	v_lshl_add_u64 v[230:231], s[48:49], 0, v[134:135]
	s_mov_b32 m0, s54
	s_nop 0
	global_load_lds_dwordx4 v[230:231], off
	s_waitcnt vmcnt(8)
	s_waitcnt lgkmcnt(0)
	s_setprio 1
	s_barrier
	v_mfma_f32_16x16x32_bf16 v[112:115], v[148:151], v[192:195], v[112:115]
	v_mfma_f32_16x16x32_bf16 v[116:119], v[168:171], v[192:195], v[116:119]
	v_mfma_f32_16x16x32_bf16 v[100:103], v[148:151], v[200:203], v[100:103]
	v_mfma_f32_16x16x32_bf16 v[96:99], v[168:171], v[200:203], v[96:99]
	v_mfma_f32_16x16x32_bf16 v[84:87], v[148:151], v[208:211], v[84:87]
	v_mfma_f32_16x16x32_bf16 v[80:83], v[168:171], v[208:211], v[80:83]
	v_mfma_f32_16x16x32_bf16 v[52:55], v[148:151], v[216:219], v[52:55]
	v_mfma_f32_16x16x32_bf16 v[48:51], v[168:171], v[216:219], v[48:51]
	v_mfma_f32_16x16x32_bf16 v[112:115], v[164:167], v[196:199], v[112:115]
	v_mfma_f32_16x16x32_bf16 v[116:119], v[172:175], v[196:199], v[116:119]
	v_mfma_f32_16x16x32_bf16 v[100:103], v[164:167], v[204:207], v[100:103]
	v_mfma_f32_16x16x32_bf16 v[96:99], v[172:175], v[204:207], v[96:99]
	v_mfma_f32_16x16x32_bf16 v[84:87], v[164:167], v[212:215], v[84:87]
	v_mfma_f32_16x16x32_bf16 v[80:83], v[172:175], v[212:215], v[80:83]
	v_mfma_f32_16x16x32_bf16 v[52:55], v[164:167], v[220:223], v[52:55]
	v_mfma_f32_16x16x32_bf16 v[48:51], v[172:175], v[220:223], v[48:51]
	s_setprio 0
	s_setprio 1
	v_mfma_f32_16x16x32_bf16 v[124:127], v[176:179], v[192:195], v[124:127]
	v_mfma_f32_16x16x32_bf16 v[120:123], v[184:187], v[192:195], v[120:123]
	v_mfma_f32_16x16x32_bf16 v[108:111], v[176:179], v[200:203], v[108:111]
	v_mfma_f32_16x16x32_bf16 v[104:107], v[184:187], v[200:203], v[104:107]
	v_mfma_f32_16x16x32_bf16 v[92:95], v[176:179], v[208:211], v[92:95]
	v_mfma_f32_16x16x32_bf16 v[88:91], v[184:187], v[208:211], v[88:91]
	v_mfma_f32_16x16x32_bf16 v[68:71], v[176:179], v[216:219], v[68:71]
	v_mfma_f32_16x16x32_bf16 v[64:67], v[184:187], v[216:219], v[64:67]
	v_mfma_f32_16x16x32_bf16 v[124:127], v[180:183], v[196:199], v[124:127]
	v_mfma_f32_16x16x32_bf16 v[120:123], v[188:191], v[196:199], v[120:123]
	v_mfma_f32_16x16x32_bf16 v[108:111], v[180:183], v[204:207], v[108:111]
	v_mfma_f32_16x16x32_bf16 v[104:107], v[188:191], v[204:207], v[104:107]
	v_mfma_f32_16x16x32_bf16 v[92:95], v[180:183], v[212:215], v[92:95]
	v_mfma_f32_16x16x32_bf16 v[88:91], v[188:191], v[212:215], v[88:91]
	v_mfma_f32_16x16x32_bf16 v[68:71], v[180:183], v[220:223], v[68:71]
	v_mfma_f32_16x16x32_bf16 v[64:67], v[188:191], v[220:223], v[64:67]
	s_barrier
	s_setprio 0
	s_add_i32 s48, s88, s97
	v_lshl_add_u64 v[152:153], v[152:153], 0, s[18:19]
	s_mov_b32 m0, s48
	ds_read_b128 v[192:195], v161 offset:49152
	ds_read_b128 v[196:199], v161 offset:50176
	ds_read_b128 v[200:203], v161 offset:51200
	ds_read_b128 v[204:207], v161 offset:52224
	ds_read_b128 v[208:211], v161 offset:53248
	ds_read_b128 v[212:215], v161 offset:54272
	ds_read_b128 v[216:219], v161 offset:55296
	ds_read_b128 v[220:223], v161 offset:56320
	global_load_lds_dwordx4 v[152:153], off
	s_add_i32 m0, s48, 0x2000
	s_add_u32 s46, s46, 0x100080
	v_lshl_add_u64 v[152:153], v[224:225], 0, s[18:19]
	s_addc_u32 s47, s47, 0
	s_add_i32 s48, s89, s97
	global_load_lds_dwordx4 v[152:153], off
	v_lshl_add_u64 v[152:153], s[46:47], 0, v[132:133]
	s_mov_b32 m0, s48
	s_nop 0
	global_load_lds_dwordx4 v[152:153], off
	v_lshl_add_u64 v[152:153], s[46:47], 0, v[136:137]
	s_add_i32 m0, s48, 0x2000
	s_nop 0
	global_load_lds_dwordx4 v[152:153], off
	v_lshl_add_u64 v[152:153], v[226:227], 0, s[18:19]
	s_mov_b32 m0, s68
	s_nop 0
	global_load_lds_dwordx4 v[152:153], off
	v_lshl_add_u64 v[152:153], v[228:229], 0, s[18:19]
	s_mov_b32 m0, s69
	s_nop 0
	global_load_lds_dwordx4 v[152:153], off
	s_waitcnt vmcnt(8)
	s_waitcnt lgkmcnt(0)
	s_setprio 1
	s_barrier
	v_mfma_f32_16x16x32_bf16 v[60:63], v[148:151], v[192:195], v[60:63]
	v_mfma_f32_16x16x32_bf16 v[56:59], v[168:171], v[192:195], v[56:59]
	v_mfma_f32_16x16x32_bf16 v[36:39], v[148:151], v[200:203], v[36:39]
	v_mfma_f32_16x16x32_bf16 v[32:35], v[168:171], v[200:203], v[32:35]
	v_mfma_f32_16x16x32_bf16 v[20:23], v[148:151], v[208:211], v[20:23]
	v_mfma_f32_16x16x32_bf16 v[16:19], v[168:171], v[208:211], v[16:19]
	v_mfma_f32_16x16x32_bf16 v[4:7], v[148:151], v[216:219], v[4:7]
	v_mfma_f32_16x16x32_bf16 v[0:3], v[168:171], v[216:219], v[0:3]
	v_mfma_f32_16x16x32_bf16 v[60:63], v[164:167], v[196:199], v[60:63]
	v_mfma_f32_16x16x32_bf16 v[56:59], v[172:175], v[196:199], v[56:59]
	v_mfma_f32_16x16x32_bf16 v[36:39], v[164:167], v[204:207], v[36:39]
	v_mfma_f32_16x16x32_bf16 v[32:35], v[172:175], v[204:207], v[32:35]
	v_mfma_f32_16x16x32_bf16 v[20:23], v[164:167], v[212:215], v[20:23]
	v_mfma_f32_16x16x32_bf16 v[16:19], v[172:175], v[212:215], v[16:19]
	v_mfma_f32_16x16x32_bf16 v[4:7], v[164:167], v[220:223], v[4:7]
	v_mfma_f32_16x16x32_bf16 v[0:3], v[172:175], v[220:223], v[0:3]
	s_setprio 0
	s_setprio 1
	v_mfma_f32_16x16x32_bf16 v[76:79], v[176:179], v[192:195], v[76:79]
	v_mfma_f32_16x16x32_bf16 v[72:75], v[184:187], v[192:195], v[72:75]
	v_mfma_f32_16x16x32_bf16 v[44:47], v[176:179], v[200:203], v[44:47]
	v_mfma_f32_16x16x32_bf16 v[40:43], v[184:187], v[200:203], v[40:43]
	v_mfma_f32_16x16x32_bf16 v[28:31], v[176:179], v[208:211], v[28:31]
	v_mfma_f32_16x16x32_bf16 v[24:27], v[184:187], v[208:211], v[24:27]
	v_mfma_f32_16x16x32_bf16 v[12:15], v[176:179], v[216:219], v[12:15]
	v_mfma_f32_16x16x32_bf16 v[8:11], v[184:187], v[216:219], v[8:11]
	v_mfma_f32_16x16x32_bf16 v[76:79], v[180:183], v[196:199], v[76:79]
	v_mfma_f32_16x16x32_bf16 v[72:75], v[188:191], v[196:199], v[72:75]
	v_mfma_f32_16x16x32_bf16 v[44:47], v[180:183], v[204:207], v[44:47]
	v_mfma_f32_16x16x32_bf16 v[40:43], v[188:191], v[204:207], v[40:43]
	v_mfma_f32_16x16x32_bf16 v[28:31], v[180:183], v[212:215], v[28:31]
	v_mfma_f32_16x16x32_bf16 v[24:27], v[188:191], v[212:215], v[24:27]
	v_mfma_f32_16x16x32_bf16 v[12:15], v[180:183], v[220:223], v[12:15]
	v_mfma_f32_16x16x32_bf16 v[8:11], v[188:191], v[220:223], v[8:11]
	s_barrier
	s_setprio 0
	s_add_u32 s85, s85, 0x100
	s_addc_u32 s86, s86, 0
	s_add_u32 s44, s44, 0x100
	s_addc_u32 s45, s45, 0
	s_cmp_ge_u32 s87, s84
	s_mov_b32 s46, s87
	s_cbranch_scc1 .Lpeel_done_3

.Lpeel_done_3:
	v_readlane_b32 s44, v254, 27
	v_readlane_b32 s45, v254, 28
	s_and_b64 vcc, exec, s[44:45]
	s_cbranch_vccz .LBB0_2297
	s_barrier
	s_cmp_lt_i32 s16, 0
	s_mov_b64 s[44:45], -1
	s_cbranch_scc1 .LBB0_2298

.LBB0_2452:
	s_cmp_lt_u32 s35, 0x3fffffff
	s_cselect_b64 s[38:39], -1, 0
	s_ashr_i32 s35, s34, 31
	s_and_b64 s[38:39], s[4:5], s[38:39]
	s_lshl_b64 s[4:5], s[34:35], 23
	s_add_u32 s4, s2, s4
	s_addc_u32 s5, s3, s5
	s_add_u32 s4, s4, s36
	s_addc_u32 s5, s5, s37
	s_and_b64 s[48:49], s[38:39], exec
	s_cselect_b32 s35, s5, s47
	s_cselect_b32 s41, s4, s46
	s_ashr_i32 s31, s30, 31
	s_lshl_b64 s[48:49], s[30:31], 23
	v_readlane_b32 s78, v254, 54
	v_readlane_b32 s79, v254, 55
	s_add_u32 s31, s78, s48
	s_addc_u32 s43, s79, s49
	s_add_u32 s36, s31, s36
	s_addc_u32 s37, s43, s37
	s_and_b64 s[48:49], s[38:39], exec
	s_cselect_b32 s31, s37, s45
	s_cselect_b32 s43, s36, s44
	s_add_i32 s75, s76, -2
	s_add_u32 s77, s44, 0x100
	s_addc_u32 s78, s45, 0
	s_add_u32 s44, s46, 0x400080
	s_addc_u32 s45, s47, 0
	s_mov_b32 s46, 0
	ds_read_b128 v[128:131], v228
	ds_read_b128 v[132:135], v228 offset:1024
	ds_read_b128 v[136:139], v228 offset:2048
	ds_read_b128 v[140:143], v228 offset:3072
	ds_read_b128 v[144:147], v229
	ds_read_b128 v[148:151], v229 offset:1024
	ds_read_b128 v[152:155], v229 offset:2048
	ds_read_b128 v[156:159], v229 offset:3072
	s_add_i32 s79, s46, 2
	s_add_u32 s47, s44, 0xffc00080
	s_addc_u32 s48, s45, -1
	s_cmp_eq_u32 s75, s46
	s_cselect_b32 s46, s43, s77
	s_cselect_b32 s49, s35, s48
	s_cselect_b32 s48, s41, s47
	s_cselect_b32 s47, s31, s78
	v_lshl_add_u64 v[208:209], s[44:45], 0, v[202:203]
	s_add_i32 m0, s94, 0xc000
	ds_read_b128 v[160:163], v230
	ds_read_b128 v[164:167], v230 offset:1024
	ds_read_b128 v[168:171], v230 offset:2048
	ds_read_b128 v[172:175], v230 offset:3072
	ds_read_b128 v[176:179], v230 offset:4096
	ds_read_b128 v[180:183], v230 offset:5120
	ds_read_b128 v[184:187], v230 offset:6144
	ds_read_b128 v[188:191], v230 offset:7168
	global_load_lds_dwordx4 v[208:209], off
	v_lshl_add_u64 v[208:209], s[44:45], 0, v[204:205]
	s_add_i32 m0, s94, 0xe000
	s_nop 0
	global_load_lds_dwordx4 v[208:209], off
	s_waitcnt vmcnt(8)
	s_waitcnt lgkmcnt(0)
	s_setprio 1
	s_barrier
	v_mfma_f32_16x16x32_bf16 v[112:115], v[128:131], v[160:163], 0
	v_mfma_f32_16x16x32_bf16 v[116:119], v[136:139], v[160:163], 0
	v_mfma_f32_16x16x32_bf16 v[100:103], v[128:131], v[168:171], 0
	v_mfma_f32_16x16x32_bf16 v[96:99], v[136:139], v[168:171], 0
	v_mfma_f32_16x16x32_bf16 v[84:87], v[128:131], v[176:179], 0
	v_mfma_f32_16x16x32_bf16 v[80:83], v[136:139], v[176:179], 0
	v_mfma_f32_16x16x32_bf16 v[52:55], v[128:131], v[184:187], 0
	v_mfma_f32_16x16x32_bf16 v[48:51], v[136:139], v[184:187], 0
	v_mfma_f32_16x16x32_bf16 v[112:115], v[132:135], v[164:167], v[112:115]
	v_mfma_f32_16x16x32_bf16 v[116:119], v[140:143], v[164:167], v[116:119]
	v_mfma_f32_16x16x32_bf16 v[100:103], v[132:135], v[172:175], v[100:103]
	v_mfma_f32_16x16x32_bf16 v[96:99], v[140:143], v[172:175], v[96:99]
	v_mfma_f32_16x16x32_bf16 v[84:87], v[132:135], v[180:183], v[84:87]
	v_mfma_f32_16x16x32_bf16 v[80:83], v[140:143], v[180:183], v[80:83]
	v_mfma_f32_16x16x32_bf16 v[52:55], v[132:135], v[188:191], v[52:55]
	v_mfma_f32_16x16x32_bf16 v[48:51], v[140:143], v[188:191], v[48:51]
	s_setprio 0
	s_setprio 1
	v_mfma_f32_16x16x32_bf16 v[124:127], v[144:147], v[160:163], 0
	v_mfma_f32_16x16x32_bf16 v[120:123], v[152:155], v[160:163], 0
	v_mfma_f32_16x16x32_bf16 v[108:111], v[144:147], v[168:171], 0
	v_mfma_f32_16x16x32_bf16 v[104:107], v[152:155], v[168:171], 0
	v_mfma_f32_16x16x32_bf16 v[92:95], v[144:147], v[176:179], 0
	v_mfma_f32_16x16x32_bf16 v[88:91], v[152:155], v[176:179], 0
	v_mfma_f32_16x16x32_bf16 v[68:71], v[144:147], v[184:187], 0
	v_mfma_f32_16x16x32_bf16 v[64:67], v[152:155], v[184:187], 0
	v_mfma_f32_16x16x32_bf16 v[124:127], v[148:151], v[164:167], v[124:127]
	v_mfma_f32_16x16x32_bf16 v[120:123], v[156:159], v[164:167], v[120:123]
	v_mfma_f32_16x16x32_bf16 v[108:111], v[148:151], v[172:175], v[108:111]
	v_mfma_f32_16x16x32_bf16 v[104:107], v[156:159], v[172:175], v[104:107]
	v_mfma_f32_16x16x32_bf16 v[92:95], v[148:151], v[180:183], v[92:95]
	v_mfma_f32_16x16x32_bf16 v[88:91], v[156:159], v[180:183], v[88:91]
	v_mfma_f32_16x16x32_bf16 v[68:71], v[148:151], v[188:191], v[68:71]
	v_mfma_f32_16x16x32_bf16 v[64:67], v[156:159], v[188:191], v[64:67]
	s_barrier
	s_setprio 0
	s_add_i32 s80, s68, s97
	v_lshl_add_u64 v[208:209], s[46:47], 0, v[194:195]
	s_mov_b32 m0, s80
	ds_read_b128 v[160:163], v230 offset:16384
	ds_read_b128 v[164:167], v230 offset:17408
	ds_read_b128 v[168:171], v230 offset:18432
	ds_read_b128 v[172:175], v230 offset:19456
	ds_read_b128 v[176:179], v230 offset:20480
	ds_read_b128 v[180:183], v230 offset:21504
	ds_read_b128 v[184:187], v230 offset:22528
	ds_read_b128 v[188:191], v230 offset:23552
	global_load_lds_dwordx4 v[208:209], off
	s_add_i32 m0, s80, 0x2000
	s_add_u32 s80, s46, 0x400000
	v_lshl_add_u64 v[210:211], s[46:47], 0, v[198:199]
	s_addc_u32 s81, s47, 0
	s_add_i32 s84, s69, s97
	global_load_lds_dwordx4 v[210:211], off
	v_lshl_add_u64 v[212:213], s[80:81], 0, v[194:195]
	s_mov_b32 m0, s84
	v_lshl_add_u64 v[214:215], s[48:49], 0, v[196:197]
	global_load_lds_dwordx4 v[212:213], off
	v_lshl_add_u64 v[212:213], s[80:81], 0, v[198:199]
	s_add_i32 m0, s84, 0x2000
	s_nop 0
	global_load_lds_dwordx4 v[212:213], off
	v_lshl_add_u64 v[212:213], s[48:49], 0, v[192:193]
	s_mov_b32 m0, s94
	s_nop 0
	global_load_lds_dwordx4 v[212:213], off
	s_mov_b32 m0, s51
	s_nop 0
	global_load_lds_dwordx4 v[214:215], off
	s_waitcnt vmcnt(8)
	s_waitcnt lgkmcnt(0)
	s_setprio 1
	s_barrier
	v_mfma_f32_16x16x32_bf16 v[60:63], v[128:131], v[160:163], 0
	v_mfma_f32_16x16x32_bf16 v[56:59], v[136:139], v[160:163], 0
	v_mfma_f32_16x16x32_bf16 v[36:39], v[128:131], v[168:171], 0
	v_mfma_f32_16x16x32_bf16 v[32:35], v[136:139], v[168:171], 0
	v_mfma_f32_16x16x32_bf16 v[20:23], v[128:131], v[176:179], 0
	v_mfma_f32_16x16x32_bf16 v[16:19], v[136:139], v[176:179], 0
	v_mfma_f32_16x16x32_bf16 v[4:7], v[128:131], v[184:187], 0
	v_mfma_f32_16x16x32_bf16 v[0:3], v[136:139], v[184:187], 0
	v_mfma_f32_16x16x32_bf16 v[60:63], v[132:135], v[164:167], v[60:63]
	v_mfma_f32_16x16x32_bf16 v[56:59], v[140:143], v[164:167], v[56:59]
	v_mfma_f32_16x16x32_bf16 v[36:39], v[132:135], v[172:175], v[36:39]
	v_mfma_f32_16x16x32_bf16 v[32:35], v[140:143], v[172:175], v[32:35]
	v_mfma_f32_16x16x32_bf16 v[20:23], v[132:135], v[180:183], v[20:23]
	v_mfma_f32_16x16x32_bf16 v[16:19], v[140:143], v[180:183], v[16:19]
	v_mfma_f32_16x16x32_bf16 v[4:7], v[132:135], v[188:191], v[4:7]
	v_mfma_f32_16x16x32_bf16 v[0:3], v[140:143], v[188:191], v[0:3]
	s_setprio 0
	s_setprio 1
	v_mfma_f32_16x16x32_bf16 v[76:79], v[144:147], v[160:163], 0
	v_mfma_f32_16x16x32_bf16 v[72:75], v[152:155], v[160:163], 0
	v_mfma_f32_16x16x32_bf16 v[44:47], v[144:147], v[168:171], 0
	v_mfma_f32_16x16x32_bf16 v[40:43], v[152:155], v[168:171], 0
	v_mfma_f32_16x16x32_bf16 v[28:31], v[144:147], v[176:179], 0
	v_mfma_f32_16x16x32_bf16 v[24:27], v[152:155], v[176:179], 0
	v_mfma_f32_16x16x32_bf16 v[12:15], v[144:147], v[184:187], 0
	v_mfma_f32_16x16x32_bf16 v[8:11], v[152:155], v[184:187], 0
	v_mfma_f32_16x16x32_bf16 v[76:79], v[148:151], v[164:167], v[76:79]
	v_mfma_f32_16x16x32_bf16 v[72:75], v[156:159], v[164:167], v[72:75]
	v_mfma_f32_16x16x32_bf16 v[44:47], v[148:151], v[172:175], v[44:47]
	v_mfma_f32_16x16x32_bf16 v[40:43], v[156:159], v[172:175], v[40:43]
	v_mfma_f32_16x16x32_bf16 v[28:31], v[148:151], v[180:183], v[28:31]
	v_mfma_f32_16x16x32_bf16 v[24:27], v[156:159], v[180:183], v[24:27]
	v_mfma_f32_16x16x32_bf16 v[12:15], v[148:151], v[188:191], v[12:15]
	v_mfma_f32_16x16x32_bf16 v[8:11], v[156:159], v[188:191], v[8:11]
	s_barrier
	s_setprio 0
	s_add_i32 s80, 0, 0x18000
	s_add_i32 s81, 0, 0x1c000
	v_add_u32_e32 v140, s80, v226
	v_add_u32_e32 v156, s81, v226
	ds_read_b128 v[128:131], v140
	ds_read_b128 v[132:135], v140 offset:1024
	ds_read_b128 v[136:139], v140 offset:2048
	ds_read_b128 v[140:143], v140 offset:3072
	ds_read_b128 v[144:147], v156
	ds_read_b128 v[148:151], v156 offset:1024
	ds_read_b128 v[152:155], v156 offset:2048
	ds_read_b128 v[156:159], v156 offset:3072
	s_add_u32 s48, s48, 0x400000
	s_addc_u32 s49, s49, 0
	s_mov_b32 m0, s52
	v_lshl_add_u64 v[216:217], s[48:49], 0, v[192:193]
	ds_read_b128 v[160:163], v230 offset:32768
	ds_read_b128 v[164:167], v230 offset:33792
	ds_read_b128 v[168:171], v230 offset:34816
	ds_read_b128 v[172:175], v230 offset:35840
	ds_read_b128 v[176:179], v230 offset:36864
	ds_read_b128 v[180:183], v230 offset:37888
	ds_read_b128 v[184:187], v230 offset:38912
	ds_read_b128 v[188:191], v230 offset:39936
	global_load_lds_dwordx4 v[216:217], off
	v_lshl_add_u64 v[216:217], s[48:49], 0, v[196:197]
	s_mov_b32 m0, s53
	s_nop 0
	global_load_lds_dwordx4 v[216:217], off
	s_waitcnt vmcnt(8)
	s_waitcnt lgkmcnt(0)
	s_setprio 1
	s_barrier
	v_mfma_f32_16x16x32_bf16 v[112:115], v[128:131], v[160:163], v[112:115]
	v_mfma_f32_16x16x32_bf16 v[116:119], v[136:139], v[160:163], v[116:119]
	v_mfma_f32_16x16x32_bf16 v[100:103], v[128:131], v[168:171], v[100:103]
	v_mfma_f32_16x16x32_bf16 v[96:99], v[136:139], v[168:171], v[96:99]
	v_mfma_f32_16x16x32_bf16 v[84:87], v[128:131], v[176:179], v[84:87]
	v_mfma_f32_16x16x32_bf16 v[80:83], v[136:139], v[176:179], v[80:83]
	v_mfma_f32_16x16x32_bf16 v[52:55], v[128:131], v[184:187], v[52:55]
	v_mfma_f32_16x16x32_bf16 v[48:51], v[136:139], v[184:187], v[48:51]
	v_mfma_f32_16x16x32_bf16 v[112:115], v[132:135], v[164:167], v[112:115]
	v_mfma_f32_16x16x32_bf16 v[116:119], v[140:143], v[164:167], v[116:119]
	v_mfma_f32_16x16x32_bf16 v[100:103], v[132:135], v[172:175], v[100:103]
	v_mfma_f32_16x16x32_bf16 v[96:99], v[140:143], v[172:175], v[96:99]
	v_mfma_f32_16x16x32_bf16 v[84:87], v[132:135], v[180:183], v[84:87]
	v_mfma_f32_16x16x32_bf16 v[80:83], v[140:143], v[180:183], v[80:83]
	v_mfma_f32_16x16x32_bf16 v[52:55], v[132:135], v[188:191], v[52:55]
	v_mfma_f32_16x16x32_bf16 v[48:51], v[140:143], v[188:191], v[48:51]
	s_setprio 0
	s_setprio 1
	v_mfma_f32_16x16x32_bf16 v[124:127], v[144:147], v[160:163], v[124:127]
	v_mfma_f32_16x16x32_bf16 v[120:123], v[152:155], v[160:163], v[120:123]
	v_mfma_f32_16x16x32_bf16 v[108:111], v[144:147], v[168:171], v[108:111]
	v_mfma_f32_16x16x32_bf16 v[104:107], v[152:155], v[168:171], v[104:107]
	v_mfma_f32_16x16x32_bf16 v[92:95], v[144:147], v[176:179], v[92:95]
	v_mfma_f32_16x16x32_bf16 v[88:91], v[152:155], v[176:179], v[88:91]
	v_mfma_f32_16x16x32_bf16 v[68:71], v[144:147], v[184:187], v[68:71]
	v_mfma_f32_16x16x32_bf16 v[64:67], v[152:155], v[184:187], v[64:67]
	v_mfma_f32_16x16x32_bf16 v[124:127], v[148:151], v[164:167], v[124:127]
	v_mfma_f32_16x16x32_bf16 v[120:123], v[156:159], v[164:167], v[120:123]
	v_mfma_f32_16x16x32_bf16 v[108:111], v[148:151], v[172:175], v[108:111]
	v_mfma_f32_16x16x32_bf16 v[104:107], v[156:159], v[172:175], v[104:107]
	v_mfma_f32_16x16x32_bf16 v[92:95], v[148:151], v[180:183], v[92:95]
	v_mfma_f32_16x16x32_bf16 v[88:91], v[156:159], v[180:183], v[88:91]
	v_mfma_f32_16x16x32_bf16 v[68:71], v[148:151], v[188:191], v[68:71]
	v_mfma_f32_16x16x32_bf16 v[64:67], v[156:159], v[188:191], v[64:67]
	s_barrier
	s_setprio 0
	s_add_i32 s48, s80, s97
	v_lshl_add_u64 v[208:209], v[208:209], 0, s[12:13]
	s_mov_b32 m0, s48
	ds_read_b128 v[160:163], v230 offset:49152
	ds_read_b128 v[164:167], v230 offset:50176
	ds_read_b128 v[168:171], v230 offset:51200
	ds_read_b128 v[172:175], v230 offset:52224
	ds_read_b128 v[176:179], v230 offset:53248
	ds_read_b128 v[180:183], v230 offset:54272
	ds_read_b128 v[184:187], v230 offset:55296
	ds_read_b128 v[188:191], v230 offset:56320
	global_load_lds_dwordx4 v[208:209], off
	s_add_i32 m0, s48, 0x2000
	s_add_u32 s46, s46, 0x400080
	v_lshl_add_u64 v[208:209], v[210:211], 0, s[12:13]
	s_addc_u32 s47, s47, 0
	s_add_i32 s48, s81, s97
	global_load_lds_dwordx4 v[208:209], off
	v_lshl_add_u64 v[208:209], s[46:47], 0, v[194:195]
	s_mov_b32 m0, s48
	s_nop 0
	global_load_lds_dwordx4 v[208:209], off
	v_lshl_add_u64 v[208:209], s[46:47], 0, v[198:199]
	s_add_i32 m0, s48, 0x2000
	s_nop 0
	global_load_lds_dwordx4 v[208:209], off
	v_lshl_add_u64 v[208:209], v[212:213], 0, s[12:13]
	s_mov_b32 m0, s54
	s_nop 0
	global_load_lds_dwordx4 v[208:209], off
	v_lshl_add_u64 v[208:209], v[214:215], 0, s[12:13]
	s_mov_b32 m0, s55
	s_nop 0
	global_load_lds_dwordx4 v[208:209], off
	s_waitcnt vmcnt(8)
	s_waitcnt lgkmcnt(0)
	s_setprio 1
	s_barrier
	v_mfma_f32_16x16x32_bf16 v[60:63], v[128:131], v[160:163], v[60:63]
	v_mfma_f32_16x16x32_bf16 v[56:59], v[136:139], v[160:163], v[56:59]
	v_mfma_f32_16x16x32_bf16 v[36:39], v[128:131], v[168:171], v[36:39]
	v_mfma_f32_16x16x32_bf16 v[32:35], v[136:139], v[168:171], v[32:35]
	v_mfma_f32_16x16x32_bf16 v[20:23], v[128:131], v[176:179], v[20:23]
	v_mfma_f32_16x16x32_bf16 v[16:19], v[136:139], v[176:179], v[16:19]
	v_mfma_f32_16x16x32_bf16 v[4:7], v[128:131], v[184:187], v[4:7]
	v_mfma_f32_16x16x32_bf16 v[0:3], v[136:139], v[184:187], v[0:3]
	v_mfma_f32_16x16x32_bf16 v[60:63], v[132:135], v[164:167], v[60:63]
	v_mfma_f32_16x16x32_bf16 v[56:59], v[140:143], v[164:167], v[56:59]
	v_mfma_f32_16x16x32_bf16 v[36:39], v[132:135], v[172:175], v[36:39]
	v_mfma_f32_16x16x32_bf16 v[32:35], v[140:143], v[172:175], v[32:35]
	v_mfma_f32_16x16x32_bf16 v[20:23], v[132:135], v[180:183], v[20:23]
	v_mfma_f32_16x16x32_bf16 v[16:19], v[140:143], v[180:183], v[16:19]
	v_mfma_f32_16x16x32_bf16 v[4:7], v[132:135], v[188:191], v[4:7]
	v_mfma_f32_16x16x32_bf16 v[0:3], v[140:143], v[188:191], v[0:3]
	s_setprio 0
	s_setprio 1
	v_mfma_f32_16x16x32_bf16 v[76:79], v[144:147], v[160:163], v[76:79]
	v_mfma_f32_16x16x32_bf16 v[72:75], v[152:155], v[160:163], v[72:75]
	v_mfma_f32_16x16x32_bf16 v[44:47], v[144:147], v[168:171], v[44:47]
	v_mfma_f32_16x16x32_bf16 v[40:43], v[152:155], v[168:171], v[40:43]
	v_mfma_f32_16x16x32_bf16 v[28:31], v[144:147], v[176:179], v[28:31]
	v_mfma_f32_16x16x32_bf16 v[24:27], v[152:155], v[176:179], v[24:27]
	v_mfma_f32_16x16x32_bf16 v[12:15], v[144:147], v[184:187], v[12:15]
	v_mfma_f32_16x16x32_bf16 v[8:11], v[152:155], v[184:187], v[8:11]
	v_mfma_f32_16x16x32_bf16 v[76:79], v[148:151], v[164:167], v[76:79]
	v_mfma_f32_16x16x32_bf16 v[72:75], v[156:159], v[164:167], v[72:75]
	v_mfma_f32_16x16x32_bf16 v[44:47], v[148:151], v[172:175], v[44:47]
	v_mfma_f32_16x16x32_bf16 v[40:43], v[156:159], v[172:175], v[40:43]
	v_mfma_f32_16x16x32_bf16 v[28:31], v[148:151], v[180:183], v[28:31]
	v_mfma_f32_16x16x32_bf16 v[24:27], v[156:159], v[180:183], v[24:27]
	v_mfma_f32_16x16x32_bf16 v[12:15], v[148:151], v[188:191], v[12:15]
	v_mfma_f32_16x16x32_bf16 v[8:11], v[156:159], v[188:191], v[8:11]
	s_barrier
	s_setprio 0
	s_add_u32 s77, s77, 0x100
	s_addc_u32 s78, s78, 0
	s_add_u32 s44, s44, 0x100
	s_addc_u32 s45, s45, 0
	s_cmp_ge_u32 s79, s76
	s_mov_b32 s46, s79
	s_cbranch_scc1 .Lpeel_done_4

.Lpeel_done_4:
	v_readlane_b32 s44, v254, 27
	v_readlane_b32 s45, v254, 28
	s_and_b64 vcc, exec, s[44:45]
	s_cbranch_vccz .LBB0_2461
	s_barrier
	s_cmp_lt_i32 s10, 0
	s_mov_b64 s[44:45], -1
	s_cbranch_scc1 .LBB0_2462
